# accumulator zero-init before the GEMM K loops with 64-bit moves, on top of v34
# speedup vs baseline: 1.0198x; 1.0024x over previous
; #define WAIT_V8(n) asm volatile("s_waitcnt vmcnt(" #n ")" ::: "memory")
; #define BAR8 __builtin_amdgcn_s_barrier()
;     ...
;   f32x4 acc[2][2][4][2];
;   {
;     float zinit = 0.f;
;     asm volatile("" : "+v"(zinit));
; #pragma unroll
;     for (int a = 0; a < 2; ++a)
; #pragma unroll
;       for (int b = 0; b < 2; ++b)
; #pragma unroll
;         for (int m = 0; m < 4; ++m)
; #pragma unroll
;           for (int n = 0; n < 2; ++n)
; #pragma unroll
;             for (int j = 0; j < 4; ++j) acc[a][b][m][n][j] = zinit;
;   }
;   bf16x8 At[4][2], B0[2][2], B1[2][2];
;   const int nt = K / 64;
;   if (!pre) {
;     STAGE8(SB8(0, 0), Bt, K, bcol, 0); STAGE8(SA8(0, 0), A, lda, brow, 0);
;     STAGE8(SB8(0, 1), Bt, K, bcol + 128, 0); STAGE8(SA8(0, 1), A, lda, brow + 128, 0);
;   }
;   if (wr == 1) BAR8;
;   WAIT_V8(4); BAR8;
;   STAGE8(SB8(1, 0), Bt, K, bcol, 1); STAGE8(SA8(1, 0), A, lda, brow, 1); STAGE8(SB8(1, 1), Bt, K, bcol + 128, 1);
;   WAIT_V8(6); BAR8;
.LBB0_191:
	s_or_b64 exec, exec, s[14:15]
	v_add_u32_e32 v164, 0x18000, v150
	s_mov_b64 s[60:61], 0x80
	v_readfirstlane_b32 s14, v164
	v_add_u32_e32 v165, 0x1a000, v150
	v_lshl_add_u64 v[10:11], v[10:11], 0, s[60:61]
	s_mov_b32 m0, s14
	v_readfirstlane_b32 s14, v165
	v_add_u32_e32 v166, 0x8000, v150
	s_waitcnt vmcnt(4)
	s_barrier
	global_load_lds_dwordx4 v[10:11], off
	v_lshl_add_u64 v[10:11], v[12:13], 0, s[60:61]
	s_mov_b32 m0, s14
	v_readfirstlane_b32 s14, v166
	v_add_u32_e32 v167, 0xa000, v150
	global_load_lds_dwordx4 v[10:11], off
	v_lshl_add_u64 v[10:11], v[14:15], 0, s[60:61]
	s_mov_b32 m0, s14
	v_readfirstlane_b32 s14, v167
	v_add_u32_e32 v168, 0x1c000, v150
	global_load_lds_dwordx4 v[10:11], off
	v_lshl_add_u64 v[10:11], v[16:17], 0, s[60:61]
	s_mov_b32 m0, s14
	v_readfirstlane_b32 s14, v168
	v_add_u32_e32 v170, 0x1e000, v150
	global_load_lds_dwordx4 v[10:11], off
	v_lshl_add_u64 v[10:11], v[18:19], 0, s[60:61]
	s_mov_b32 m0, s14
	v_readfirstlane_b32 s14, v170
	global_load_lds_dwordx4 v[10:11], off
	v_lshl_add_u64 v[10:11], v[20:21], 0, s[60:61]
	s_mov_b32 m0, s14
	v_and_b32_e32 v147, 15, v3
	global_load_lds_dwordx4 v[10:11], off
	v_bfe_u32 v148, v3, 4, 2
	v_lshlrev_b32_e32 v10, 4, v148
	v_lshlrev_b32_e32 v11, 6, v147
	v_lshlrev_b32_e32 v14, 2, v3
	v_or_b32_e32 v13, v10, v11
	v_and_b32_e32 v14, 32, v14
	s_mov_b32 s14, 0x10000
	v_bitop3_b32 v16, v13, s14, v14 bitop3:0xde
	s_mov_b32 s14, 0x14000
	v_bitop3_b32 v15, v10, v14, v11 bitop3:0x36
	v_bitop3_b32 v17, v13, s14, v14 bitop3:0xde
	s_mov_b32 s14, 0x18000
	v_lshlrev_b32_e32 v11, 6, v3
	v_bitop3_b32 v18, v13, s14, v14 bitop3:0xde
	s_mov_b32 s14, 0x1c000
	v_and_b32_e32 v11, 0x3c0, v11
	v_bitop3_b32 v13, v13, s14, v14 bitop3:0xde
	v_bitop3_b32 v14, v11, v14, v10 bitop3:0x36
	v_lshl_add_u64 v[10:11], s[30:31], 0, v[136:137]
	v_lshl_add_u64 v[10:11], v[10:11], 0, v[8:9]
	v_lshl_add_u64 v[138:139], s[12:13], 0, v[10:11]
	v_lshl_add_u64 v[10:11], s[30:31], 0, v[132:133]
	v_lshl_add_u64 v[10:11], v[10:11], 0, v[6:7]
	v_lshl_add_u64 v[140:141], s[12:13], 0, v[10:11]
	v_lshl_add_u64 v[10:11], s[56:57], 0, v[132:133]
	v_lshl_add_u64 v[6:7], v[10:11], 0, v[6:7]
	v_bfe_u32 v146, v3, 6, 2
	s_waitcnt vmcnt(6)
	v_lshlrev_b32_e32 v149, 6, v5
	v_lshlrev_b32_e32 v5, 13, v5
	v_lshl_add_u64 v[142:143], s[46:47], 0, v[6:7]
	v_lshl_add_u64 v[6:7], s[56:57], 0, v[136:137]
	v_lshlrev_b32_e32 v12, 12, v146
	v_or_b32_e32 v19, 0x800, v5
	v_or_b32_e32 v20, 0x1000, v5
	v_or_b32_e32 v21, 0x1800, v5
	v_lshl_add_u64 v[6:7], v[6:7], 0, v[8:9]
	v_lshl_add_u64 v[144:145], s[46:47], 0, v[6:7]
	s_mov_b32 s14, -2
	s_mov_b64 s[12:13], 0
	v_add_u32_e32 v173, v16, v12
	v_add_u32_e32 v156, v15, v5
	v_add_u32_e32 v154, v14, v19
	v_add_u32_e32 v153, v14, v20
	v_add_u32_e32 v152, v14, v21
	v_add_u32_e32 v172, 0xc000, v150
	v_add_u32_e32 v171, 0xe000, v150
	v_add_u32_e32 v169, v17, v12
	v_add_u32_e32 v159, v18, v12
	v_add_u32_e32 v158, v13, v12
	v_mov_b32_e32 v5, v4
	v_mov_b64_e32 v[6:7], v[4:5]
	v_mov_b64_e32 v[8:9], v[4:5]
	v_mov_b64_e32 v[10:11], v[4:5]
	v_mov_b64_e32 v[12:13], v[4:5]
	v_mov_b64_e32 v[14:15], v[4:5]
	v_mov_b64_e32 v[16:17], v[4:5]
	v_mov_b64_e32 v[18:19], v[4:5]
	v_mov_b64_e32 v[20:21], v[4:5]
	v_mov_b64_e32 v[22:23], v[4:5]
	v_mov_b64_e32 v[24:25], v[4:5]
	v_mov_b64_e32 v[26:27], v[4:5]
	v_mov_b64_e32 v[28:29], v[4:5]
	v_mov_b64_e32 v[30:31], v[4:5]
	v_mov_b64_e32 v[32:33], v[4:5]
	v_mov_b64_e32 v[34:35], v[4:5]
	v_mov_b64_e32 v[36:37], v[4:5]
	v_mov_b64_e32 v[38:39], v[4:5]
	v_mov_b64_e32 v[40:41], v[4:5]
	v_mov_b64_e32 v[42:43], v[4:5]
	v_mov_b64_e32 v[44:45], v[4:5]
	v_mov_b64_e32 v[46:47], v[4:5]
	v_mov_b64_e32 v[48:49], v[4:5]
	v_mov_b64_e32 v[50:51], v[4:5]
	v_mov_b64_e32 v[52:53], v[4:5]
	v_mov_b64_e32 v[54:55], v[4:5]
	v_mov_b64_e32 v[56:57], v[4:5]
	v_mov_b64_e32 v[58:59], v[4:5]
	v_mov_b64_e32 v[60:61], v[4:5]
	v_mov_b64_e32 v[62:63], v[4:5]
	v_mov_b64_e32 v[64:65], v[4:5]
	v_mov_b64_e32 v[66:67], v[4:5]
	v_mov_b64_e32 v[68:69], v[4:5]
	v_mov_b64_e32 v[70:71], v[4:5]
	v_mov_b64_e32 v[72:73], v[4:5]
	v_mov_b64_e32 v[74:75], v[4:5]
	v_mov_b64_e32 v[76:77], v[4:5]
	v_mov_b64_e32 v[78:79], v[4:5]
	v_mov_b64_e32 v[80:81], v[4:5]
	v_mov_b64_e32 v[82:83], v[4:5]
	v_mov_b64_e32 v[84:85], v[4:5]
	v_mov_b64_e32 v[86:87], v[4:5]
	v_mov_b64_e32 v[88:89], v[4:5]
	v_mov_b64_e32 v[90:91], v[4:5]
	v_mov_b64_e32 v[92:93], v[4:5]
	v_mov_b64_e32 v[94:95], v[4:5]
	v_mov_b64_e32 v[96:97], v[4:5]
	v_mov_b64_e32 v[98:99], v[4:5]
	v_mov_b64_e32 v[100:101], v[4:5]
	v_mov_b64_e32 v[102:103], v[4:5]
	v_mov_b64_e32 v[104:105], v[4:5]
	v_mov_b64_e32 v[106:107], v[4:5]
	v_mov_b64_e32 v[108:109], v[4:5]
	v_mov_b64_e32 v[110:111], v[4:5]
	v_mov_b64_e32 v[112:113], v[4:5]
	v_mov_b64_e32 v[114:115], v[4:5]
	v_mov_b64_e32 v[116:117], v[4:5]
	v_mov_b64_e32 v[118:119], v[4:5]
	v_mov_b64_e32 v[120:121], v[4:5]
	v_mov_b64_e32 v[122:123], v[4:5]
	v_mov_b64_e32 v[124:125], v[4:5]
	v_mov_b64_e32 v[126:127], v[4:5]
	v_mov_b64_e32 v[128:129], v[4:5]
	v_mov_b64_e32 v[130:131], v[4:5]
	s_mov_b64 s[60:61], 0xc000100
	s_mov_b64 s[62:63], 0xc040100
	s_mov_b64 s[64:65], 0xc000180
	s_mov_b64 s[66:67], 0xc040180
	s_barrier

; #define WAIT_V8(n) asm volatile("s_waitcnt vmcnt(" #n ")" ::: "memory")
; #define BAR8 __builtin_amdgcn_s_barrier()
;     ...
;   f32x4 acc[2][2][4][2];
;   {
;     float zinit = 0.f;
;     asm volatile("" : "+v"(zinit));
; #pragma unroll
;     for (int a = 0; a < 2; ++a)
; #pragma unroll
;       for (int b = 0; b < 2; ++b)
; #pragma unroll
;         for (int m = 0; m < 4; ++m)
; #pragma unroll
;           for (int n = 0; n < 2; ++n)
; #pragma unroll
;             for (int j = 0; j < 4; ++j) acc[a][b][m][n][j] = zinit;
;   }
;   bf16x8 At[4][2], B0[2][2], B1[2][2];
;   const int nt = K / 64;
;   if (!pre) {
;     STAGE8(SB8(0, 0), Bt, K, bcol, 0); STAGE8(SA8(0, 0), A, lda, brow, 0);
;     STAGE8(SB8(0, 1), Bt, K, bcol + 128, 0); STAGE8(SA8(0, 1), A, lda, brow + 128, 0);
;   }
;   if (wr == 1) BAR8;
;   WAIT_V8(4); BAR8;
;   STAGE8(SB8(1, 0), Bt, K, bcol, 1); STAGE8(SA8(1, 0), A, lda, brow, 1); STAGE8(SB8(1, 1), Bt, K, bcol + 128, 1);
;   WAIT_V8(6); BAR8;
.LBB0_241:
	s_or_b64 exec, exec, s[20:21]
	v_add_u32_e32 v164, 0x18000, v150
	s_mov_b64 s[20:21], 0x80
	v_readfirstlane_b32 s1, v164
	v_add_u32_e32 v165, 0x1a000, v150
	v_lshl_add_u64 v[10:11], v[10:11], 0, s[20:21]
	s_mov_b32 m0, s1
	v_readfirstlane_b32 s1, v165
	v_add_u32_e32 v166, 0x8000, v150
	s_waitcnt vmcnt(4)
	s_barrier
	global_load_lds_dwordx4 v[10:11], off
	v_lshl_add_u64 v[10:11], v[12:13], 0, s[20:21]
	s_mov_b32 m0, s1
	v_readfirstlane_b32 s1, v166
	v_add_u32_e32 v167, 0xa000, v150
	global_load_lds_dwordx4 v[10:11], off
	v_lshl_add_u64 v[10:11], v[14:15], 0, s[20:21]
	s_mov_b32 m0, s1
	v_readfirstlane_b32 s1, v167
	v_add_u32_e32 v169, 0x1c000, v150
	global_load_lds_dwordx4 v[10:11], off
	v_lshl_add_u64 v[10:11], v[16:17], 0, s[20:21]
	s_mov_b32 m0, s1
	v_readfirstlane_b32 s1, v169
	v_add_u32_e32 v170, 0x1e000, v150
	global_load_lds_dwordx4 v[10:11], off
	v_lshl_add_u64 v[10:11], v[18:19], 0, s[20:21]
	s_mov_b32 m0, s1
	v_readfirstlane_b32 s1, v170
	global_load_lds_dwordx4 v[10:11], off
	v_lshl_add_u64 v[10:11], v[20:21], 0, s[20:21]
	s_mov_b32 m0, s1
	v_and_b32_e32 v147, 15, v3
	global_load_lds_dwordx4 v[10:11], off
	v_bfe_u32 v148, v3, 4, 2
	v_lshlrev_b32_e32 v10, 4, v148
	v_lshlrev_b32_e32 v11, 6, v147
	v_lshlrev_b32_e32 v14, 2, v3
	v_or_b32_e32 v13, v10, v11
	v_and_b32_e32 v14, 32, v14
	s_mov_b32 s1, 0x10000
	v_bitop3_b32 v16, v13, s1, v14 bitop3:0xde
	s_mov_b32 s1, 0x14000
	v_bitop3_b32 v15, v10, v14, v11 bitop3:0x36
	v_bitop3_b32 v17, v13, s1, v14 bitop3:0xde
	s_mov_b32 s1, 0x18000
	v_lshlrev_b32_e32 v11, 6, v3
	v_bitop3_b32 v18, v13, s1, v14 bitop3:0xde
	s_mov_b32 s1, 0x1c000
	v_and_b32_e32 v11, 0x3c0, v11
	v_bitop3_b32 v13, v13, s1, v14 bitop3:0xde
	v_bitop3_b32 v14, v11, v14, v10 bitop3:0x36
	v_lshl_add_u64 v[10:11], s[30:31], 0, v[136:137]
	v_lshl_add_u64 v[10:11], v[10:11], 0, v[8:9]
	v_lshl_add_u64 v[138:139], s[14:15], 0, v[10:11]
	v_lshl_add_u64 v[10:11], s[30:31], 0, v[132:133]
	v_lshl_add_u64 v[10:11], v[10:11], 0, v[6:7]
	v_lshl_add_u64 v[140:141], s[14:15], 0, v[10:11]
	v_lshl_add_u64 v[10:11], s[56:57], 0, v[132:133]
	v_lshl_add_u64 v[6:7], v[10:11], 0, v[6:7]
	v_bfe_u32 v146, v3, 6, 2
	s_waitcnt vmcnt(6)
	v_lshlrev_b32_e32 v149, 6, v5
	v_lshlrev_b32_e32 v5, 13, v5
	v_lshl_add_u64 v[142:143], s[46:47], 0, v[6:7]
	v_lshl_add_u64 v[6:7], s[56:57], 0, v[136:137]
	v_lshlrev_b32_e32 v12, 12, v146
	v_or_b32_e32 v19, 0x800, v5
	v_or_b32_e32 v20, 0x1000, v5
	v_or_b32_e32 v21, 0x1800, v5
	v_lshl_add_u64 v[6:7], v[6:7], 0, v[8:9]
	v_lshl_add_u64 v[144:145], s[46:47], 0, v[6:7]
	s_mov_b32 s1, -2
	s_mov_b64 s[14:15], 0
	v_add_u32_e32 v171, v16, v12
	v_add_u32_e32 v156, v15, v5
	v_add_u32_e32 v154, v14, v19
	v_add_u32_e32 v153, v14, v20
	v_add_u32_e32 v152, v14, v21
	v_add_u32_e32 v168, v17, v12
	v_add_u32_e32 v159, v18, v12
	v_add_u32_e32 v157, v13, v12
	v_mov_b32_e32 v5, v4
	v_mov_b64_e32 v[6:7], v[4:5]
	v_mov_b64_e32 v[8:9], v[4:5]
	v_mov_b64_e32 v[10:11], v[4:5]
	v_mov_b64_e32 v[12:13], v[4:5]
	v_mov_b64_e32 v[14:15], v[4:5]
	v_mov_b64_e32 v[16:17], v[4:5]
	v_mov_b64_e32 v[18:19], v[4:5]
	v_mov_b64_e32 v[20:21], v[4:5]
	v_mov_b64_e32 v[22:23], v[4:5]
	v_mov_b64_e32 v[24:25], v[4:5]
	v_mov_b64_e32 v[26:27], v[4:5]
	v_mov_b64_e32 v[28:29], v[4:5]
	v_mov_b64_e32 v[30:31], v[4:5]
	v_mov_b64_e32 v[32:33], v[4:5]
	v_mov_b64_e32 v[34:35], v[4:5]
	v_mov_b64_e32 v[36:37], v[4:5]
	v_mov_b64_e32 v[38:39], v[4:5]
	v_mov_b64_e32 v[40:41], v[4:5]
	v_mov_b64_e32 v[42:43], v[4:5]
	v_mov_b64_e32 v[44:45], v[4:5]
	v_mov_b64_e32 v[46:47], v[4:5]
	v_mov_b64_e32 v[48:49], v[4:5]
	v_mov_b64_e32 v[50:51], v[4:5]
	v_mov_b64_e32 v[52:53], v[4:5]
	v_mov_b64_e32 v[54:55], v[4:5]
	v_mov_b64_e32 v[56:57], v[4:5]
	v_mov_b64_e32 v[58:59], v[4:5]
	v_mov_b64_e32 v[60:61], v[4:5]
	v_mov_b64_e32 v[62:63], v[4:5]
	v_mov_b64_e32 v[64:65], v[4:5]
	v_mov_b64_e32 v[66:67], v[4:5]
	v_mov_b64_e32 v[68:69], v[4:5]
	v_mov_b64_e32 v[70:71], v[4:5]
	v_mov_b64_e32 v[72:73], v[4:5]
	v_mov_b64_e32 v[74:75], v[4:5]
	v_mov_b64_e32 v[76:77], v[4:5]
	v_mov_b64_e32 v[78:79], v[4:5]
	v_mov_b64_e32 v[80:81], v[4:5]
	v_mov_b64_e32 v[82:83], v[4:5]
	v_mov_b64_e32 v[84:85], v[4:5]
	v_mov_b64_e32 v[86:87], v[4:5]
	v_mov_b64_e32 v[88:89], v[4:5]
	v_mov_b64_e32 v[90:91], v[4:5]
	v_mov_b64_e32 v[92:93], v[4:5]
	v_mov_b64_e32 v[94:95], v[4:5]
	v_mov_b64_e32 v[96:97], v[4:5]
	v_mov_b64_e32 v[98:99], v[4:5]
	v_mov_b64_e32 v[100:101], v[4:5]
	v_mov_b64_e32 v[102:103], v[4:5]
	v_mov_b64_e32 v[104:105], v[4:5]
	v_mov_b64_e32 v[106:107], v[4:5]
	v_mov_b64_e32 v[108:109], v[4:5]
	v_mov_b64_e32 v[110:111], v[4:5]
	v_mov_b64_e32 v[112:113], v[4:5]
	v_mov_b64_e32 v[114:115], v[4:5]
	v_mov_b64_e32 v[116:117], v[4:5]
	v_mov_b64_e32 v[118:119], v[4:5]
	v_mov_b64_e32 v[120:121], v[4:5]
	v_mov_b64_e32 v[122:123], v[4:5]
	v_mov_b64_e32 v[124:125], v[4:5]
	v_mov_b64_e32 v[126:127], v[4:5]
	v_mov_b64_e32 v[128:129], v[4:5]
	v_mov_b64_e32 v[130:131], v[4:5]
	s_mov_b64 s[30:31], 0xc000100
	s_mov_b64 s[56:57], 0xc040100
	s_mov_b64 s[58:59], 0xc000180
	s_mov_b64 s[60:61], 0xc040180
	s_barrier

; #define WAIT_V8(n) asm volatile("s_waitcnt vmcnt(" #n ")" ::: "memory")
; #define BAR8 __builtin_amdgcn_s_barrier()
;     ...
;   f32x4 acc[2][2][4][2];
;   {
;     float zinit = 0.f;
;     asm volatile("" : "+v"(zinit));
; #pragma unroll
;     for (int a = 0; a < 2; ++a)
; #pragma unroll
;       for (int b = 0; b < 2; ++b)
; #pragma unroll
;         for (int m = 0; m < 4; ++m)
; #pragma unroll
;           for (int n = 0; n < 2; ++n)
; #pragma unroll
;             for (int j = 0; j < 4; ++j) acc[a][b][m][n][j] = zinit;
;   }
;   bf16x8 At[4][2], B0[2][2], B1[2][2];
;   const int nt = K / 64;
;   if (!pre) {
;     STAGE8(SB8(0, 0), Bt, K, bcol, 0); STAGE8(SA8(0, 0), A, lda, brow, 0);
;     STAGE8(SB8(0, 1), Bt, K, bcol + 128, 0); STAGE8(SA8(0, 1), A, lda, brow + 128, 0);
;   }
;   if (wr == 1) BAR8;
;   WAIT_V8(4); BAR8;
;   STAGE8(SB8(1, 0), Bt, K, bcol, 1); STAGE8(SA8(1, 0), A, lda, brow, 1); STAGE8(SB8(1, 1), Bt, K, bcol + 128, 1);
;   WAIT_V8(6); BAR8;
.LBB0_907:
	s_or_b64 exec, exec, s[12:13]
	s_lshl_b32 s29, s20, 11
	s_waitcnt vmcnt(0)
	v_add_u32_e32 v164, 0x18000, v150
	s_and_b32 s36, s29, 0x1f80000
	s_mov_b64 s[38:39], 0x80
	v_readfirstlane_b32 s29, v164
	v_add_u32_e32 v165, 0x1a000, v150
	v_lshl_add_u64 v[14:15], v[14:15], 0, s[38:39]
	s_mov_b32 m0, s29
	v_readfirstlane_b32 s29, v165
	v_add_u32_e32 v166, 0x8000, v150
	s_waitcnt vmcnt(4)
	s_barrier
	global_load_lds_dwordx4 v[14:15], off
	v_lshl_add_u64 v[14:15], v[18:19], 0, s[38:39]
	s_mov_b32 m0, s29
	v_readfirstlane_b32 s29, v166
	v_add_u32_e32 v168, 0xa000, v150
	global_load_lds_dwordx4 v[14:15], off
	v_lshl_add_u64 v[14:15], v[20:21], 0, s[38:39]
	s_mov_b32 m0, s29
	v_readfirstlane_b32 s29, v168
	v_add_u32_e32 v169, 0x1c000, v150
	global_load_lds_dwordx4 v[14:15], off
	v_lshl_add_u64 v[14:15], v[22:23], 0, s[38:39]
	s_mov_b32 m0, s29
	v_readfirstlane_b32 s29, v169
	v_add_u32_e32 v170, 0x1e000, v150
	global_load_lds_dwordx4 v[14:15], off
	v_lshl_add_u64 v[14:15], v[26:27], 0, s[38:39]
	s_mov_b32 m0, s29
	v_readfirstlane_b32 s29, v170
	global_load_lds_dwordx4 v[14:15], off
	v_lshl_add_u64 v[14:15], v[28:29], 0, s[38:39]
	s_mov_b32 m0, s29
	v_and_b32_e32 v147, 15, v3
	global_load_lds_dwordx4 v[14:15], off
	v_bfe_u32 v148, v3, 4, 2
	v_lshlrev_b32_e32 v14, 4, v148
	v_lshlrev_b32_e32 v15, 6, v147
	v_lshlrev_b32_e32 v18, 2, v3
	v_lshlrev_b64 v[136:137], 10, v[16:17]
	v_or_b32_e32 v17, v14, v15
	v_and_b32_e32 v18, 32, v18
	s_mov_b32 s29, 0x10000
	s_and_b32 s12, s21, 0xffffff00
	v_bitop3_b32 v20, v17, s29, v18 bitop3:0xde
	s_mov_b32 s29, 0x14000
	s_ashr_i32 s13, s12, 31
	v_readlane_b32 s40, v254, 35
	v_bitop3_b32 v19, v14, v18, v15 bitop3:0x36
	v_bitop3_b32 v21, v17, s29, v18 bitop3:0xde
	s_mov_b32 s29, 0x18000
	v_lshlrev_b32_e32 v15, 6, v3
	s_lshl_b64 s[12:13], s[12:13], 11
	s_mov_b32 s37, s40
	v_bitop3_b32 v22, v17, s29, v18 bitop3:0xde
	s_mov_b32 s29, 0x1c000
	v_and_b32_e32 v15, 0x3c0, v15
	v_bitop3_b32 v17, v17, s29, v18 bitop3:0xde
	v_bitop3_b32 v18, v15, v18, v14 bitop3:0x36
	v_lshl_add_u64 v[14:15], s[12:13], 0, v[6:7]
	v_lshl_add_u64 v[6:7], s[36:37], 0, v[6:7]
	v_lshl_add_u64 v[14:15], v[14:15], 0, v[8:9]
	v_lshl_add_u64 v[6:7], v[6:7], 0, v[8:9]
	v_bfe_u32 v146, v3, 6, 2
	s_waitcnt vmcnt(6)
	v_lshlrev_b32_e32 v149, 6, v5
	v_lshlrev_b32_e32 v5, 13, v5
	v_lshl_add_u64 v[138:139], s[4:5], 0, v[14:15]
	v_lshl_add_u64 v[14:15], s[12:13], 0, v[10:11]
	v_lshl_add_u64 v[142:143], s[2:3], 0, v[6:7]
	v_lshl_add_u64 v[6:7], s[36:37], 0, v[10:11]
	v_lshlrev_b64 v[134:135], 10, v[24:25]
	v_readlane_b32 s41, v254, 36
	v_readlane_b32 s42, v254, 37
	v_readlane_b32 s43, v254, 38
	v_lshlrev_b32_e32 v16, 12, v146
	v_or_b32_e32 v23, 0x800, v5
	v_or_b32_e32 v24, 0x1000, v5
	v_or_b32_e32 v25, 0x1800, v5
	v_lshl_add_u64 v[14:15], v[14:15], 0, v[12:13]
	v_lshl_add_u64 v[6:7], v[6:7], 0, v[12:13]
	v_lshl_add_u64 v[140:141], s[4:5], 0, v[14:15]
	v_lshl_add_u64 v[144:145], s[2:3], 0, v[6:7]
	s_mov_b32 s29, -2
	s_mov_b64 s[12:13], 0
	v_add_u32_e32 v171, v20, v16
	v_add_u32_e32 v156, v19, v5
	v_add_u32_e32 v155, v18, v23
	v_add_u32_e32 v154, v18, v24
	v_add_u32_e32 v153, v18, v25
	v_add_u32_e32 v167, v21, v16
	v_add_u32_e32 v160, v22, v16
	v_add_u32_e32 v158, v17, v16
	v_mov_b32_e32 v5, v4
	v_mov_b64_e32 v[6:7], v[4:5]
	v_mov_b64_e32 v[8:9], v[4:5]
	v_mov_b64_e32 v[10:11], v[4:5]
	v_mov_b64_e32 v[12:13], v[4:5]
	v_mov_b64_e32 v[14:15], v[4:5]
	v_mov_b64_e32 v[16:17], v[4:5]
	v_mov_b64_e32 v[18:19], v[4:5]
	v_mov_b64_e32 v[20:21], v[4:5]
	v_mov_b64_e32 v[22:23], v[4:5]
	v_mov_b64_e32 v[24:25], v[4:5]
	v_mov_b64_e32 v[26:27], v[4:5]
	v_mov_b64_e32 v[28:29], v[4:5]
	v_mov_b64_e32 v[30:31], v[4:5]
	v_mov_b64_e32 v[32:33], v[4:5]
	v_mov_b64_e32 v[34:35], v[4:5]
	v_mov_b64_e32 v[36:37], v[4:5]
	v_mov_b64_e32 v[38:39], v[4:5]
	v_mov_b64_e32 v[40:41], v[4:5]
	v_mov_b64_e32 v[42:43], v[4:5]
	v_mov_b64_e32 v[44:45], v[4:5]
	v_mov_b64_e32 v[46:47], v[4:5]
	v_mov_b64_e32 v[48:49], v[4:5]
	v_mov_b64_e32 v[50:51], v[4:5]
	v_mov_b64_e32 v[52:53], v[4:5]
	v_mov_b64_e32 v[54:55], v[4:5]
	v_mov_b64_e32 v[56:57], v[4:5]
	v_mov_b64_e32 v[58:59], v[4:5]
	v_mov_b64_e32 v[60:61], v[4:5]
	v_mov_b64_e32 v[62:63], v[4:5]
	v_mov_b64_e32 v[64:65], v[4:5]
	v_mov_b64_e32 v[66:67], v[4:5]
	v_mov_b64_e32 v[68:69], v[4:5]
	v_mov_b64_e32 v[70:71], v[4:5]
	v_mov_b64_e32 v[72:73], v[4:5]
	v_mov_b64_e32 v[74:75], v[4:5]
	v_mov_b64_e32 v[76:77], v[4:5]
	v_mov_b64_e32 v[78:79], v[4:5]
	v_mov_b64_e32 v[80:81], v[4:5]
	v_mov_b64_e32 v[82:83], v[4:5]
	v_mov_b64_e32 v[84:85], v[4:5]
	v_mov_b64_e32 v[86:87], v[4:5]
	v_mov_b64_e32 v[88:89], v[4:5]
	v_mov_b64_e32 v[90:91], v[4:5]
	v_mov_b64_e32 v[92:93], v[4:5]
	v_mov_b64_e32 v[94:95], v[4:5]
	v_mov_b64_e32 v[96:97], v[4:5]
	v_mov_b64_e32 v[98:99], v[4:5]
	v_mov_b64_e32 v[100:101], v[4:5]
	v_mov_b64_e32 v[102:103], v[4:5]
	v_mov_b64_e32 v[104:105], v[4:5]
	v_mov_b64_e32 v[106:107], v[4:5]
	v_mov_b64_e32 v[108:109], v[4:5]
	v_mov_b64_e32 v[110:111], v[4:5]
	v_mov_b64_e32 v[112:113], v[4:5]
	v_mov_b64_e32 v[114:115], v[4:5]
	v_mov_b64_e32 v[116:117], v[4:5]
	v_mov_b64_e32 v[118:119], v[4:5]
	v_mov_b64_e32 v[120:121], v[4:5]
	v_mov_b64_e32 v[122:123], v[4:5]
	v_mov_b64_e32 v[124:125], v[4:5]
	v_mov_b64_e32 v[126:127], v[4:5]
	v_mov_b64_e32 v[128:129], v[4:5]
	v_mov_b64_e32 v[130:131], v[4:5]
	s_mov_b64 s[36:37], 0x6040080
	s_mov_b64 s[38:39], 0xc4a0100
	s_mov_b64 s[40:41], 0x6000100
	s_mov_b64 s[42:43], 0xc4e0100
	s_mov_b64 s[44:45], 0x6040100
	s_mov_b64 s[46:47], 0xc4a0180
	s_mov_b64 s[48:49], 0x6000180
	s_mov_b64 s[50:51], 0xc4e0180
	s_barrier

; #define WAIT_V8(n) asm volatile("s_waitcnt vmcnt(" #n ")" ::: "memory")
; #define BAR8 __builtin_amdgcn_s_barrier()
;     ...
;   f32x4 acc[2][2][4][2];
;   {
;     float zinit = 0.f;
;     asm volatile("" : "+v"(zinit));
; #pragma unroll
;     for (int a = 0; a < 2; ++a)
; #pragma unroll
;       for (int b = 0; b < 2; ++b)
; #pragma unroll
;         for (int m = 0; m < 4; ++m)
; #pragma unroll
;           for (int n = 0; n < 2; ++n)
; #pragma unroll
;             for (int j = 0; j < 4; ++j) acc[a][b][m][n][j] = zinit;
;   }
;   bf16x8 At[4][2], B0[2][2], B1[2][2];
;   const int nt = K / 64;
;   if (!pre) {
;     STAGE8(SB8(0, 0), Bt, K, bcol, 0); STAGE8(SA8(0, 0), A, lda, brow, 0);
;     STAGE8(SB8(0, 1), Bt, K, bcol + 128, 0); STAGE8(SA8(0, 1), A, lda, brow + 128, 0);
;   }
;   if (wr == 1) BAR8;
;   WAIT_V8(4); BAR8;
;   STAGE8(SB8(1, 0), Bt, K, bcol, 1); STAGE8(SA8(1, 0), A, lda, brow, 1); STAGE8(SB8(1, 1), Bt, K, bcol + 128, 1);
;   WAIT_V8(6); BAR8;
.LBB0_1004:
	s_or_b64 exec, exec, s[20:21]
	v_readlane_b32 s40, v254, 35
	s_lshl_b32 s20, s36, 10
	v_readlane_b32 s42, v254, 37
	v_readlane_b32 s43, v254, 38
	s_waitcnt vmcnt(0)
	v_add_u32_e32 v164, 0x18000, v150
	s_and_b32 s20, s20, 0xfffc0000
	s_mov_b32 s21, s40
	s_mov_b64 s[42:43], 0x80
	v_readfirstlane_b32 s40, v164
	v_add_u32_e32 v165, 0x1a000, v150
	s_and_b32 s1, s27, 7
	s_add_i32 s20, s20, 0xffc00000
	v_lshl_add_u64 v[10:11], v[10:11], 0, s[42:43]
	s_mov_b32 m0, s40
	v_readfirstlane_b32 s40, v165
	v_add_u32_e32 v166, 0x8000, v150
	s_lshl_b32 s1, s1, 19
	s_lshl_b64 s[20:21], s[20:21], 1
	s_waitcnt vmcnt(4)
	s_barrier
	global_load_lds_dwordx4 v[10:11], off
	v_lshl_add_u64 v[10:11], v[12:13], 0, s[42:43]
	s_mov_b32 m0, s40
	v_readfirstlane_b32 s40, v166
	v_add_u32_e32 v167, 0xa000, v150
	global_load_lds_dwordx4 v[10:11], off
	v_lshl_add_u64 v[10:11], v[16:17], 0, s[42:43]
	s_mov_b32 m0, s40
	v_readfirstlane_b32 s40, v167
	s_add_u32 s14, s14, 0x40080
	global_load_lds_dwordx4 v[10:11], off
	v_lshl_add_u64 v[10:11], v[14:15], 0, s[42:43]
	s_mov_b32 m0, s40
	s_addc_u32 s15, s15, 0
	v_add_u32_e32 v169, 0x1c000, v150
	global_load_lds_dwordx4 v[10:11], off
	v_lshl_add_u64 v[10:11], s[14:15], 0, v[132:133]
	v_readfirstlane_b32 s40, v169
	v_lshl_add_u64 v[10:11], v[10:11], 0, v[6:7]
	s_mov_b32 m0, s40
	v_add_u32_e32 v170, 0x1e000, v150
	global_load_lds_dwordx4 v[10:11], off
	v_lshl_add_u64 v[10:11], s[14:15], 0, v[136:137]
	v_readfirstlane_b32 s14, v170
	v_lshl_add_u64 v[10:11], v[10:11], 0, v[8:9]
	s_mov_b32 m0, s14
	v_and_b32_e32 v147, 15, v3
	global_load_lds_dwordx4 v[10:11], off
	v_bfe_u32 v148, v3, 4, 2
	v_lshlrev_b32_e32 v11, 4, v148
	v_lshlrev_b32_e32 v12, 6, v147
	v_lshlrev_b32_e32 v14, 2, v3
	v_or_b32_e32 v13, v11, v12
	v_and_b32_e32 v14, 32, v14
	s_mov_b32 s14, 0x10000
	v_bitop3_b32 v15, v13, s14, v14 bitop3:0xde
	s_mov_b32 s14, 0x14000
	s_add_u32 s12, s12, s1
	v_bitop3_b32 v16, v13, s14, v14 bitop3:0xde
	s_mov_b32 s14, 0x18000
	v_lshlrev_b32_e32 v18, 6, v3
	s_addc_u32 s13, s13, 0
	v_lshl_add_u64 v[8:9], v[136:137], 0, v[8:9]
	v_lshl_add_u64 v[6:7], v[132:133], 0, v[6:7]
	v_bfe_u32 v146, v3, 6, 2
	s_waitcnt vmcnt(6)
	v_lshlrev_b32_e32 v149, 6, v5
	v_bitop3_b32 v17, v13, s14, v14 bitop3:0xde
	s_mov_b32 s14, 0x1c000
	v_lshlrev_b32_e32 v5, 13, v5
	v_and_b32_e32 v18, 0x3c0, v18
	v_lshl_add_u64 v[138:139], s[12:13], 0, v[8:9]
	v_lshl_add_u64 v[140:141], s[12:13], 0, v[6:7]
	s_add_u32 s12, s4, s20
	v_readlane_b32 s41, v254, 36
	v_lshlrev_b32_e32 v10, 12, v146
	v_bitop3_b32 v12, v11, v14, v12 bitop3:0x36
	v_bitop3_b32 v13, v13, s14, v14 bitop3:0xde
	v_bitop3_b32 v11, v18, v14, v11 bitop3:0x36
	v_or_b32_e32 v14, 0x800, v5
	v_or_b32_e32 v18, 0x1000, v5
	v_or_b32_e32 v19, 0x1800, v5
	s_addc_u32 s13, s5, s21
	v_lshl_add_u64 v[142:143], s[12:13], 0, v[6:7]
	v_lshl_add_u64 v[144:145], s[12:13], 0, v[8:9]
	s_mov_b32 s1, -2
	s_mov_b64 s[12:13], 0
	v_add_u32_e32 v171, v15, v10
	v_add_u32_e32 v156, v12, v5
	v_add_u32_e32 v155, v11, v14
	v_add_u32_e32 v154, v11, v18
	v_add_u32_e32 v153, v11, v19
	v_add_u32_e32 v168, v16, v10
	v_add_u32_e32 v161, v17, v10
	v_add_u32_e32 v158, v13, v10
	v_mov_b32_e32 v5, v4
	v_mov_b64_e32 v[6:7], v[4:5]
	v_mov_b64_e32 v[8:9], v[4:5]
	v_mov_b64_e32 v[10:11], v[4:5]
	v_mov_b64_e32 v[12:13], v[4:5]
	v_mov_b64_e32 v[14:15], v[4:5]
	v_mov_b64_e32 v[16:17], v[4:5]
	v_mov_b64_e32 v[18:19], v[4:5]
	v_mov_b64_e32 v[20:21], v[4:5]
	v_mov_b64_e32 v[22:23], v[4:5]
	v_mov_b64_e32 v[24:25], v[4:5]
	v_mov_b64_e32 v[26:27], v[4:5]
	v_mov_b64_e32 v[28:29], v[4:5]
	v_mov_b64_e32 v[30:31], v[4:5]
	v_mov_b64_e32 v[32:33], v[4:5]
	v_mov_b64_e32 v[34:35], v[4:5]
	v_mov_b64_e32 v[36:37], v[4:5]
	v_mov_b64_e32 v[38:39], v[4:5]
	v_mov_b64_e32 v[40:41], v[4:5]
	v_mov_b64_e32 v[42:43], v[4:5]
	v_mov_b64_e32 v[44:45], v[4:5]
	v_mov_b64_e32 v[46:47], v[4:5]
	v_mov_b64_e32 v[48:49], v[4:5]
	v_mov_b64_e32 v[50:51], v[4:5]
	v_mov_b64_e32 v[52:53], v[4:5]
	v_mov_b64_e32 v[54:55], v[4:5]
	v_mov_b64_e32 v[56:57], v[4:5]
	v_mov_b64_e32 v[58:59], v[4:5]
	v_mov_b64_e32 v[60:61], v[4:5]
	v_mov_b64_e32 v[62:63], v[4:5]
	v_mov_b64_e32 v[64:65], v[4:5]
	v_mov_b64_e32 v[66:67], v[4:5]
	v_mov_b64_e32 v[68:69], v[4:5]
	v_mov_b64_e32 v[70:71], v[4:5]
	v_mov_b64_e32 v[72:73], v[4:5]
	v_mov_b64_e32 v[74:75], v[4:5]
	v_mov_b64_e32 v[76:77], v[4:5]
	v_mov_b64_e32 v[78:79], v[4:5]
	v_mov_b64_e32 v[80:81], v[4:5]
	v_mov_b64_e32 v[82:83], v[4:5]
	v_mov_b64_e32 v[84:85], v[4:5]
	v_mov_b64_e32 v[86:87], v[4:5]
	v_mov_b64_e32 v[88:89], v[4:5]
	v_mov_b64_e32 v[90:91], v[4:5]
	v_mov_b64_e32 v[92:93], v[4:5]
	v_mov_b64_e32 v[94:95], v[4:5]
	v_mov_b64_e32 v[96:97], v[4:5]
	v_mov_b64_e32 v[98:99], v[4:5]
	v_mov_b64_e32 v[100:101], v[4:5]
	v_mov_b64_e32 v[102:103], v[4:5]
	v_mov_b64_e32 v[104:105], v[4:5]
	v_mov_b64_e32 v[106:107], v[4:5]
	v_mov_b64_e32 v[108:109], v[4:5]
	v_mov_b64_e32 v[110:111], v[4:5]
	v_mov_b64_e32 v[112:113], v[4:5]
	v_mov_b64_e32 v[114:115], v[4:5]
	v_mov_b64_e32 v[116:117], v[4:5]
	v_mov_b64_e32 v[118:119], v[4:5]
	v_mov_b64_e32 v[120:121], v[4:5]
	v_mov_b64_e32 v[122:123], v[4:5]
	v_mov_b64_e32 v[124:125], v[4:5]
	v_mov_b64_e32 v[126:127], v[4:5]
	v_mov_b64_e32 v[128:129], v[4:5]
	v_mov_b64_e32 v[130:131], v[4:5]
	s_mov_b64 s[20:21], 0xb840080
	s_mov_b64 s[40:41], 0xc7a0100
	s_mov_b64 s[42:43], 0xb800100
	s_mov_b64 s[44:45], 0xc7e0100
	s_mov_b64 s[46:47], 0xb840100
	s_mov_b64 s[48:49], 0xc7a0180
	s_mov_b64 s[50:51], 0xb800180
	s_mov_b64 s[52:53], 0xc7e0180
	s_barrier

; #define WAIT_V8(n) asm volatile("s_waitcnt vmcnt(" #n ")" ::: "memory")
; #define BAR8 __builtin_amdgcn_s_barrier()
;     ...
;   f32x4 acc[2][2][4][2];
;   {
;     float zinit = 0.f;
;     asm volatile("" : "+v"(zinit));
; #pragma unroll
;     for (int a = 0; a < 2; ++a)
; #pragma unroll
;       for (int b = 0; b < 2; ++b)
; #pragma unroll
;         for (int m = 0; m < 4; ++m)
; #pragma unroll
;           for (int n = 0; n < 2; ++n)
; #pragma unroll
;             for (int j = 0; j < 4; ++j) acc[a][b][m][n][j] = zinit;
;   }
;   bf16x8 At[4][2], B0[2][2], B1[2][2];
;   const int nt = K / 64;
;   if (!pre) {
;     STAGE8(SB8(0, 0), Bt, K, bcol, 0); STAGE8(SA8(0, 0), A, lda, brow, 0);
;     STAGE8(SB8(0, 1), Bt, K, bcol + 128, 0); STAGE8(SA8(0, 1), A, lda, brow + 128, 0);
;   }
;   if (wr == 1) BAR8;
;   WAIT_V8(4); BAR8;
;   STAGE8(SB8(1, 0), Bt, K, bcol, 1); STAGE8(SA8(1, 0), A, lda, brow, 1); STAGE8(SB8(1, 1), Bt, K, bcol + 128, 1);
;   WAIT_V8(6); BAR8;
.LBB0_1014:
	s_or_b64 exec, exec, s[14:15]
	v_readlane_b32 s40, v254, 35
	v_readlane_b32 s42, v254, 37
	v_readlane_b32 s43, v254, 38
	s_waitcnt vmcnt(0)
	v_add_u32_e32 v164, 0x18000, v150
	s_mov_b64 s[42:43], 0x80
	v_readfirstlane_b32 s21, v164
	v_add_u32_e32 v165, 0x1a000, v150
	v_lshl_add_u64 v[10:11], v[10:11], 0, s[42:43]
	s_mov_b32 m0, s21
	v_readfirstlane_b32 s21, v165
	v_add_u32_e32 v166, 0x8000, v150
	s_waitcnt vmcnt(4)
	s_barrier
	global_load_lds_dwordx4 v[10:11], off
	v_lshl_add_u64 v[10:11], v[12:13], 0, s[42:43]
	s_mov_b32 m0, s21
	v_readfirstlane_b32 s21, v166
	v_add_u32_e32 v167, 0xa000, v150
	global_load_lds_dwordx4 v[10:11], off
	v_lshl_add_u64 v[10:11], v[14:15], 0, s[42:43]
	s_mov_b32 m0, s21
	v_readfirstlane_b32 s21, v167
	v_add_u32_e32 v169, 0x1c000, v150
	global_load_lds_dwordx4 v[10:11], off
	v_lshl_add_u64 v[10:11], v[16:17], 0, s[42:43]
	s_mov_b32 m0, s21
	v_readfirstlane_b32 s21, v169
	v_add_u32_e32 v170, 0x1e000, v150
	global_load_lds_dwordx4 v[10:11], off
	v_lshl_add_u64 v[10:11], v[18:19], 0, s[42:43]
	s_mov_b32 m0, s21
	v_readfirstlane_b32 s21, v170
	global_load_lds_dwordx4 v[10:11], off
	v_lshl_add_u64 v[10:11], v[20:21], 0, s[42:43]
	s_mov_b32 m0, s21
	v_and_b32_e32 v147, 15, v3
	global_load_lds_dwordx4 v[10:11], off
	v_bfe_u32 v148, v3, 4, 2
	v_lshlrev_b32_e32 v10, 4, v148
	v_lshlrev_b32_e32 v11, 6, v147
	v_lshlrev_b32_e32 v14, 2, v3
	v_or_b32_e32 v13, v10, v11
	v_and_b32_e32 v14, 32, v14
	s_mov_b32 s21, 0x10000
	v_bitop3_b32 v16, v13, s21, v14 bitop3:0xde
	s_mov_b32 s21, 0x14000
	s_and_b32 s14, s27, 63
	v_bitop3_b32 v15, v10, v14, v11 bitop3:0x36
	v_bitop3_b32 v17, v13, s21, v14 bitop3:0xde
	s_mov_b32 s21, 0x18000
	v_lshlrev_b32_e32 v11, 6, v3
	s_lshl_b32 s14, s14, 19
	s_mov_b32 s15, s40
	v_bitop3_b32 v18, v13, s21, v14 bitop3:0xde
	s_mov_b32 s21, 0x1c000
	v_and_b32_e32 v11, 0x3c0, v11
	v_bitop3_b32 v13, v13, s21, v14 bitop3:0xde
	v_bitop3_b32 v14, v11, v14, v10 bitop3:0x36
	v_lshl_add_u64 v[10:11], s[14:15], 0, v[136:137]
	v_readlane_b32 s41, v254, 36
	s_and_b32 s40, s33, 0xffffff00
	v_lshl_add_u64 v[10:11], v[10:11], 0, v[8:9]
	s_ashr_i32 s41, s40, 31
	v_lshl_add_u64 v[138:139], s[12:13], 0, v[10:11]
	v_lshl_add_u64 v[10:11], s[14:15], 0, v[132:133]
	s_lshl_b64 s[40:41], s[40:41], 11
	v_lshl_add_u64 v[10:11], v[10:11], 0, v[6:7]
	v_lshl_add_u64 v[140:141], s[12:13], 0, v[10:11]
	v_lshl_add_u64 v[10:11], s[40:41], 0, v[132:133]
	v_lshl_add_u64 v[6:7], v[10:11], 0, v[6:7]
	v_bfe_u32 v146, v3, 6, 2
	s_waitcnt vmcnt(6)
	v_lshlrev_b32_e32 v149, 6, v5
	v_lshlrev_b32_e32 v5, 13, v5
	v_lshl_add_u64 v[142:143], s[4:5], 0, v[6:7]
	v_lshl_add_u64 v[6:7], s[40:41], 0, v[136:137]
	v_lshlrev_b32_e32 v12, 12, v146
	v_or_b32_e32 v19, 0x800, v5
	v_or_b32_e32 v20, 0x1000, v5
	v_or_b32_e32 v21, 0x1800, v5
	v_lshl_add_u64 v[6:7], v[6:7], 0, v[8:9]
	v_lshl_add_u64 v[144:145], s[4:5], 0, v[6:7]
	s_mov_b32 s14, -2
	s_mov_b64 s[12:13], 0
	v_add_u32_e32 v171, v16, v12
	v_add_u32_e32 v156, v15, v5
	v_add_u32_e32 v155, v14, v19
	v_add_u32_e32 v154, v14, v20
	v_add_u32_e32 v153, v14, v21
	v_add_u32_e32 v168, v17, v12
	v_add_u32_e32 v161, v18, v12
	v_add_u32_e32 v158, v13, v12
	v_mov_b32_e32 v5, v4
	v_mov_b64_e32 v[6:7], v[4:5]
	v_mov_b64_e32 v[8:9], v[4:5]
	v_mov_b64_e32 v[10:11], v[4:5]
	v_mov_b64_e32 v[12:13], v[4:5]
	v_mov_b64_e32 v[14:15], v[4:5]
	v_mov_b64_e32 v[16:17], v[4:5]
	v_mov_b64_e32 v[18:19], v[4:5]
	v_mov_b64_e32 v[20:21], v[4:5]
	v_mov_b64_e32 v[22:23], v[4:5]
	v_mov_b64_e32 v[24:25], v[4:5]
	v_mov_b64_e32 v[26:27], v[4:5]
	v_mov_b64_e32 v[28:29], v[4:5]
	v_mov_b64_e32 v[30:31], v[4:5]
	v_mov_b64_e32 v[32:33], v[4:5]
	v_mov_b64_e32 v[34:35], v[4:5]
	v_mov_b64_e32 v[36:37], v[4:5]
	v_mov_b64_e32 v[38:39], v[4:5]
	v_mov_b64_e32 v[40:41], v[4:5]
	v_mov_b64_e32 v[42:43], v[4:5]
	v_mov_b64_e32 v[44:45], v[4:5]
	v_mov_b64_e32 v[46:47], v[4:5]
	v_mov_b64_e32 v[48:49], v[4:5]
	v_mov_b64_e32 v[50:51], v[4:5]
	v_mov_b64_e32 v[52:53], v[4:5]
	v_mov_b64_e32 v[54:55], v[4:5]
	v_mov_b64_e32 v[56:57], v[4:5]
	v_mov_b64_e32 v[58:59], v[4:5]
	v_mov_b64_e32 v[60:61], v[4:5]
	v_mov_b64_e32 v[62:63], v[4:5]
	v_mov_b64_e32 v[64:65], v[4:5]
	v_mov_b64_e32 v[66:67], v[4:5]
	v_mov_b64_e32 v[68:69], v[4:5]
	v_mov_b64_e32 v[70:71], v[4:5]
	v_mov_b64_e32 v[72:73], v[4:5]
	v_mov_b64_e32 v[74:75], v[4:5]
	v_mov_b64_e32 v[76:77], v[4:5]
	v_mov_b64_e32 v[78:79], v[4:5]
	v_mov_b64_e32 v[80:81], v[4:5]
	v_mov_b64_e32 v[82:83], v[4:5]
	v_mov_b64_e32 v[84:85], v[4:5]
	v_mov_b64_e32 v[86:87], v[4:5]
	v_mov_b64_e32 v[88:89], v[4:5]
	v_mov_b64_e32 v[90:91], v[4:5]
	v_mov_b64_e32 v[92:93], v[4:5]
	v_mov_b64_e32 v[94:95], v[4:5]
	v_mov_b64_e32 v[96:97], v[4:5]
	v_mov_b64_e32 v[98:99], v[4:5]
	v_mov_b64_e32 v[100:101], v[4:5]
	v_mov_b64_e32 v[102:103], v[4:5]
	v_mov_b64_e32 v[104:105], v[4:5]
	v_mov_b64_e32 v[106:107], v[4:5]
	v_mov_b64_e32 v[108:109], v[4:5]
	v_mov_b64_e32 v[110:111], v[4:5]
	v_mov_b64_e32 v[112:113], v[4:5]
	v_mov_b64_e32 v[114:115], v[4:5]
	v_mov_b64_e32 v[116:117], v[4:5]
	v_mov_b64_e32 v[118:119], v[4:5]
	v_mov_b64_e32 v[120:121], v[4:5]
	v_mov_b64_e32 v[122:123], v[4:5]
	v_mov_b64_e32 v[124:125], v[4:5]
	v_mov_b64_e32 v[126:127], v[4:5]
	v_mov_b64_e32 v[128:129], v[4:5]
	v_mov_b64_e32 v[130:131], v[4:5]
	s_mov_b64 s[40:41], 0xc6a0100
	s_mov_b64 s[42:43], 0xc6e0100
	s_mov_b64 s[44:45], 0xc6a0180
	s_mov_b64 s[46:47], 0xc6e0180
	s_barrier

; #define WAIT_V8(n) asm volatile("s_waitcnt vmcnt(" #n ")" ::: "memory")
; #define BAR8 __builtin_amdgcn_s_barrier()
;     ...
;   f32x4 acc[2][2][4][2];
;   {
;     float zinit = 0.f;
;     asm volatile("" : "+v"(zinit));
; #pragma unroll
;     for (int a = 0; a < 2; ++a)
; #pragma unroll
;       for (int b = 0; b < 2; ++b)
; #pragma unroll
;         for (int m = 0; m < 4; ++m)
; #pragma unroll
;           for (int n = 0; n < 2; ++n)
; #pragma unroll
;             for (int j = 0; j < 4; ++j) acc[a][b][m][n][j] = zinit;
;   }
;   bf16x8 At[4][2], B0[2][2], B1[2][2];
;   const int nt = K / 64;
;   if (!pre) {
;     STAGE8(SB8(0, 0), Bt, K, bcol, 0); STAGE8(SA8(0, 0), A, lda, brow, 0);
;     STAGE8(SB8(0, 1), Bt, K, bcol + 128, 0); STAGE8(SA8(0, 1), A, lda, brow + 128, 0);
;   }
;   if (wr == 1) BAR8;
;   WAIT_V8(4); BAR8;
;   STAGE8(SB8(1, 0), Bt, K, bcol, 1); STAGE8(SA8(1, 0), A, lda, brow, 1); STAGE8(SB8(1, 1), Bt, K, bcol + 128, 1);
;   WAIT_V8(6); BAR8;
.LBB0_1151:
	s_or_b64 exec, exec, s[12:13]
	s_lshl_b32 s29, s20, 10
	v_add_u32_e32 v164, 0x18000, v150
	s_and_b32 s36, s29, 0xfc0000
	s_mov_b64 s[38:39], 0x80
	v_readfirstlane_b32 s29, v164
	v_add_u32_e32 v165, 0x1a000, v150
	v_lshl_add_u64 v[14:15], v[14:15], 0, s[38:39]
	s_mov_b32 m0, s29
	v_readfirstlane_b32 s29, v165
	v_add_u32_e32 v166, 0x8000, v150
	s_waitcnt vmcnt(4)
	s_barrier
	global_load_lds_dwordx4 v[14:15], off
	v_lshl_add_u64 v[14:15], v[18:19], 0, s[38:39]
	s_mov_b32 m0, s29
	v_readfirstlane_b32 s29, v166
	v_add_u32_e32 v168, 0xa000, v150
	global_load_lds_dwordx4 v[14:15], off
	v_lshl_add_u64 v[14:15], v[20:21], 0, s[38:39]
	s_mov_b32 m0, s29
	v_readfirstlane_b32 s29, v168
	v_add_u32_e32 v169, 0x1c000, v150
	global_load_lds_dwordx4 v[14:15], off
	v_lshl_add_u64 v[14:15], v[22:23], 0, s[38:39]
	s_mov_b32 m0, s29
	v_readfirstlane_b32 s29, v169
	v_add_u32_e32 v170, 0x1e000, v150
	global_load_lds_dwordx4 v[14:15], off
	v_lshl_add_u64 v[14:15], v[26:27], 0, s[38:39]
	s_mov_b32 m0, s29
	v_readfirstlane_b32 s29, v170
	global_load_lds_dwordx4 v[14:15], off
	v_lshl_add_u64 v[14:15], v[28:29], 0, s[38:39]
	s_mov_b32 m0, s29
	v_and_b32_e32 v147, 15, v3
	global_load_lds_dwordx4 v[14:15], off
	v_bfe_u32 v148, v3, 4, 2
	v_lshlrev_b32_e32 v14, 4, v148
	v_lshlrev_b32_e32 v15, 6, v147
	v_lshlrev_b32_e32 v18, 2, v3
	v_lshlrev_b64 v[136:137], 9, v[16:17]
	v_or_b32_e32 v17, v14, v15
	v_and_b32_e32 v18, 32, v18
	s_mov_b32 s29, 0x10000
	s_and_b32 s12, s21, 0xffffff00
	v_bitop3_b32 v20, v17, s29, v18 bitop3:0xde
	s_mov_b32 s29, 0x14000
	s_ashr_i32 s13, s12, 31
	v_readlane_b32 s40, v254, 35
	v_bitop3_b32 v19, v14, v18, v15 bitop3:0x36
	v_bitop3_b32 v21, v17, s29, v18 bitop3:0xde
	s_mov_b32 s29, 0x18000
	v_lshlrev_b32_e32 v15, 6, v3
	s_lshl_b64 s[12:13], s[12:13], 10
	s_mov_b32 s37, s40
	v_bitop3_b32 v22, v17, s29, v18 bitop3:0xde
	s_mov_b32 s29, 0x1c000
	v_and_b32_e32 v15, 0x3c0, v15
	v_bitop3_b32 v17, v17, s29, v18 bitop3:0xde
	v_bitop3_b32 v18, v15, v18, v14 bitop3:0x36
	v_lshl_add_u64 v[14:15], s[12:13], 0, v[6:7]
	v_lshl_add_u64 v[6:7], s[36:37], 0, v[6:7]
	v_lshl_add_u64 v[14:15], v[14:15], 0, v[8:9]
	v_lshl_add_u64 v[6:7], v[6:7], 0, v[8:9]
	v_bfe_u32 v146, v3, 6, 2
	s_waitcnt vmcnt(6)
	v_lshlrev_b32_e32 v149, 6, v5
	v_lshlrev_b32_e32 v5, 13, v5
	v_lshl_add_u64 v[138:139], s[4:5], 0, v[14:15]
	v_lshl_add_u64 v[14:15], s[12:13], 0, v[10:11]
	v_lshl_add_u64 v[142:143], s[2:3], 0, v[6:7]
	v_lshl_add_u64 v[6:7], s[36:37], 0, v[10:11]
	v_lshlrev_b64 v[134:135], 9, v[24:25]
	v_readlane_b32 s41, v254, 36
	v_readlane_b32 s42, v254, 37
	v_readlane_b32 s43, v254, 38
	v_lshlrev_b32_e32 v16, 12, v146
	v_or_b32_e32 v23, 0x800, v5
	v_or_b32_e32 v24, 0x1000, v5
	v_or_b32_e32 v25, 0x1800, v5
	v_lshl_add_u64 v[14:15], v[14:15], 0, v[12:13]
	v_lshl_add_u64 v[6:7], v[6:7], 0, v[12:13]
	v_lshl_add_u64 v[140:141], s[4:5], 0, v[14:15]
	v_lshl_add_u64 v[144:145], s[2:3], 0, v[6:7]
	s_mov_b32 s29, -2
	s_mov_b64 s[12:13], 0
	v_add_u32_e32 v171, v20, v16
	v_add_u32_e32 v156, v19, v5
	v_add_u32_e32 v155, v18, v23
	v_add_u32_e32 v154, v18, v24
	v_add_u32_e32 v153, v18, v25
	v_add_u32_e32 v167, v21, v16
	v_add_u32_e32 v160, v22, v16
	v_add_u32_e32 v158, v17, v16
	v_mov_b32_e32 v5, v4
	v_mov_b64_e32 v[6:7], v[4:5]
	v_mov_b64_e32 v[8:9], v[4:5]
	v_mov_b64_e32 v[10:11], v[4:5]
	v_mov_b64_e32 v[12:13], v[4:5]
	v_mov_b64_e32 v[14:15], v[4:5]
	v_mov_b64_e32 v[16:17], v[4:5]
	v_mov_b64_e32 v[18:19], v[4:5]
	v_mov_b64_e32 v[20:21], v[4:5]
	v_mov_b64_e32 v[22:23], v[4:5]
	v_mov_b64_e32 v[24:25], v[4:5]
	v_mov_b64_e32 v[26:27], v[4:5]
	v_mov_b64_e32 v[28:29], v[4:5]
	v_mov_b64_e32 v[30:31], v[4:5]
	v_mov_b64_e32 v[32:33], v[4:5]
	v_mov_b64_e32 v[34:35], v[4:5]
	v_mov_b64_e32 v[36:37], v[4:5]
	v_mov_b64_e32 v[38:39], v[4:5]
	v_mov_b64_e32 v[40:41], v[4:5]
	v_mov_b64_e32 v[42:43], v[4:5]
	v_mov_b64_e32 v[44:45], v[4:5]
	v_mov_b64_e32 v[46:47], v[4:5]
	v_mov_b64_e32 v[48:49], v[4:5]
	v_mov_b64_e32 v[50:51], v[4:5]
	v_mov_b64_e32 v[52:53], v[4:5]
	v_mov_b64_e32 v[54:55], v[4:5]
	v_mov_b64_e32 v[56:57], v[4:5]
	v_mov_b64_e32 v[58:59], v[4:5]
	v_mov_b64_e32 v[60:61], v[4:5]
	v_mov_b64_e32 v[62:63], v[4:5]
	v_mov_b64_e32 v[64:65], v[4:5]
	v_mov_b64_e32 v[66:67], v[4:5]
	v_mov_b64_e32 v[68:69], v[4:5]
	v_mov_b64_e32 v[70:71], v[4:5]
	v_mov_b64_e32 v[72:73], v[4:5]
	v_mov_b64_e32 v[74:75], v[4:5]
	v_mov_b64_e32 v[76:77], v[4:5]
	v_mov_b64_e32 v[78:79], v[4:5]
	v_mov_b64_e32 v[80:81], v[4:5]
	v_mov_b64_e32 v[82:83], v[4:5]
	v_mov_b64_e32 v[84:85], v[4:5]
	v_mov_b64_e32 v[86:87], v[4:5]
	v_mov_b64_e32 v[88:89], v[4:5]
	v_mov_b64_e32 v[90:91], v[4:5]
	v_mov_b64_e32 v[92:93], v[4:5]
	v_mov_b64_e32 v[94:95], v[4:5]
	v_mov_b64_e32 v[96:97], v[4:5]
	v_mov_b64_e32 v[98:99], v[4:5]
	v_mov_b64_e32 v[100:101], v[4:5]
	v_mov_b64_e32 v[102:103], v[4:5]
	v_mov_b64_e32 v[104:105], v[4:5]
	v_mov_b64_e32 v[106:107], v[4:5]
	v_mov_b64_e32 v[108:109], v[4:5]
	v_mov_b64_e32 v[110:111], v[4:5]
	v_mov_b64_e32 v[112:113], v[4:5]
	v_mov_b64_e32 v[114:115], v[4:5]
	v_mov_b64_e32 v[116:117], v[4:5]
	v_mov_b64_e32 v[118:119], v[4:5]
	v_mov_b64_e32 v[120:121], v[4:5]
	v_mov_b64_e32 v[122:123], v[4:5]
	v_mov_b64_e32 v[124:125], v[4:5]
	v_mov_b64_e32 v[126:127], v[4:5]
	v_mov_b64_e32 v[128:129], v[4:5]
	v_mov_b64_e32 v[130:131], v[4:5]
	s_mov_b64 s[36:37], 0x3020080
	s_mov_b64 s[38:39], 0xc9a0100
	s_mov_b64 s[40:41], 0x3000100
	s_mov_b64 s[42:43], 0xc9c0100
	s_mov_b64 s[44:45], 0x3020100
	s_mov_b64 s[46:47], 0xc9a0180
	s_mov_b64 s[48:49], 0x3000180
	s_mov_b64 s[50:51], 0xc9c0180
	s_barrier

; #define WAIT_V0() asm volatile("s_waitcnt vmcnt(0)" ::: "memory")
; template <int EPI, int BN, bool F16>
; DI void gemm_tile(const bf16_t* __restrict__ A, int lda, const bf16_t* __restrict__ W, int K, int m0, int n0, const Ep& e) {
;     ...
;   f32x16 acc[MI][2];
; #pragma unroll
;   for (int i = 0; i < MI; ++i)
; #pragma unroll
;     for (int j = 0; j < 2; ++j)
; #pragma unroll
;       for (int k = 0; k < 16; ++k) acc[i][j][k] = 0.f;
;   const int grow = w * 8 + (l >> 3);
;   const int gch = (l & 7) ^ ((grow >> 1) & 7);
;   const bf16_t* ap = A + (size_t)(m0 + grow) * lda + gch * 8;
;   const bf16_t* wp = W + (size_t)(n0 + grow) * K + gch * 8;
;   unsigned char* lbase = smem + w * 1024;
;   const int sw = (r >> 1) & 7;
;   const unsigned char* ab = smem + (wm * (MI * 32) + r) * 128;
;   const unsigned char* bb = smem + 32768 + (wn * 64 + r) * 128;
;   const int nk = K >> 6;
;     ...
;   G_STAGE(0, 0)
;   WAIT_V0();
;   __syncthreads();
.LBB0_1245:
	s_mov_b32 s0, 25
	s_ashr_i32 s1, s0, 31
	s_lshr_b32 s12, s24, 8
	s_lshl_b64 s[0:1], s[0:1], 3
	s_add_u32 s0, s70, s0
	s_addc_u32 s1, s71, s1
	s_load_dwordx2 s[0:1], s[0:1], 0x0
	s_mov_b32 s2, 25
	s_waitcnt lgkmcnt(0)
	s_add_u32 s38, s0, 0xf640000
	s_addc_u32 s39, s1, 0
	s_ashr_i32 s3, s2, 31
	s_lshl_b64 s[0:1], s[2:3], 3
	s_add_u32 s0, s70, s0
	s_addc_u32 s1, s71, s1
	s_load_dwordx2 s[0:1], s[0:1], 0x0
	s_waitcnt lgkmcnt(0)
	s_add_u32 s30, s0, 0x2000000
	s_addc_u32 s31, s1, 0
	s_cmpk_gt_i32 s25, 0x4ff
	s_mov_b64 s[0:1], -1
	s_cbranch_scc0 .LBB0_1253
	s_mov_b32 s0, 25
	s_ashr_i32 s1, s0, 31
	s_and_b32 s27, s12, 63
	s_and_b32 s29, s21, 0x7fffff80
	s_lshl_b64 s[0:1], s[0:1], 3
	s_add_u32 s0, s70, s0
	s_addc_u32 s1, s71, s1
	s_load_dwordx2 s[2:3], s[0:1], 0x0
	s_lshl_b32 s0, s25, 8
	v_mov_b32_e32 v3, v224
	s_and_b32 s13, s0, 0x3f00
	s_lshl_b32 s0, s25, 1
	s_and_b32 s0, s0, 0x7fffff80
	v_ashrrev_i32_e32 v8, 6, v3
	v_lshlrev_b32_e32 v9, 3, v8
	v_bfe_u32 v10, v3, 3, 3
	s_addk_i32 s0, 0xa00
	v_or_b32_e32 v6, v9, v10
	v_lshrrev_b32_e32 v11, 1, v6
	v_add_u32_e32 v0, s13, v6
	v_add_u32_e32 v6, s0, v6
	v_xor_b32_e32 v4, v11, v3
	v_ashrrev_i32_e32 v1, 31, v0
	v_ashrrev_i32_e32 v7, 31, v6
	v_lshlrev_b64 v[0:1], 11, v[0:1]
	v_lshlrev_b32_e32 v4, 4, v4
	v_lshlrev_b64 v[6:7], 11, v[6:7]
	s_waitcnt lgkmcnt(0)
	v_lshl_add_u64 v[0:1], s[2:3], 0, v[0:1]
	v_and_b32_e32 v4, 0x70, v4
	v_mov_b32_e32 v5, v2
	v_lshl_add_u64 v[6:7], s[4:5], 0, v[6:7]
	v_lshl_add_u64 v[0:1], v[0:1], 0, v[4:5]
	v_lshl_add_u64 v[4:5], v[6:7], 0, v[4:5]
	v_lshlrev_b32_e32 v79, 10, v8
	v_ashrrev_i32_e32 v6, 1, v3
	v_and_b32_e32 v76, 31, v3
	v_and_b32_e32 v77, 0xffffffc0, v6
	v_add_u32_e32 v82, 0x8000, v79
	v_readfirstlane_b32 s1, v79
	v_or_b32_e32 v6, v77, v76
	s_mov_b32 m0, s1
	v_readfirstlane_b32 s1, v82
	v_add_u32_e32 v83, 0x2000, v79
	v_lshlrev_b32_e32 v80, 7, v6
	v_lshlrev_b32_e32 v6, 7, v3
	global_load_lds_dwordx4 v[0:1], off
	s_mov_b32 m0, s1
	s_mov_b64 s[14:15], 0x20000
	v_readfirstlane_b32 s1, v83
	v_add_u32_e32 v84, 0xa000, v79
	v_and_b32_e32 v81, 0x2f80, v6
	global_load_lds_dwordx4 v[4:5], off
	v_lshl_add_u64 v[6:7], v[0:1], 0, s[14:15]
	s_mov_b32 m0, s1
	v_readfirstlane_b32 s1, v84
	v_add_u32_e32 v85, 0x4000, v79
	global_load_lds_dwordx4 v[6:7], off
	v_lshl_add_u64 v[4:5], v[4:5], 0, s[14:15]
	s_mov_b32 m0, s1
	s_mov_b64 s[14:15], 0x40000
	v_readfirstlane_b32 s1, v85
	v_add_u32_e32 v86, 0x6000, v79
	global_load_lds_dwordx4 v[4:5], off
	v_lshl_add_u64 v[4:5], v[0:1], 0, s[14:15]
	s_mov_b32 m0, s1
	s_mov_b64 s[14:15], 0x60000
	v_readfirstlane_b32 s1, v86
	global_load_lds_dwordx4 v[4:5], off
	v_lshl_add_u64 v[0:1], v[0:1], 0, s[14:15]
	s_mov_b32 m0, s1
	v_lshl_or_b32 v4, s27, 8, v10
	global_load_lds_dwordx4 v[0:1], off
	v_add_u32_e32 v4, v4, v9
	v_ashrrev_i32_e32 v5, 31, v4
	v_lshlrev_b64 v[4:5], 11, v[4:5]
	v_lshrrev_b32_e32 v8, 1, v3
	v_bfe_u32 v78, v3, 5, 1
	v_lshl_add_u64 v[68:69], s[2:3], 0, v[4:5]
	v_or_b32_e32 v4, s29, v10
	s_movk_i32 s1, 0xa00
	v_bfe_u32 v0, v3, 1, 3
	v_bitop3_b32 v1, v78, v8, 7 bitop3:0x78
	v_add3_u32 v4, v4, v9, s1
	v_lshlrev_b32_e32 v89, 4, v1
	v_bitop3_b32 v1, v78, v0, 2 bitop3:0x36
	v_ashrrev_i32_e32 v5, 31, v4
	s_waitcnt vmcnt(0)
	v_lshlrev_b32_e32 v90, 4, v1
	v_bitop3_b32 v1, v78, v0, 4 bitop3:0x36
	v_bitop3_b32 v0, v78, v0, 6 bitop3:0x36
	v_lshlrev_b64 v[4:5], 11, v[4:5]
	v_lshlrev_b32_e32 v92, 4, v0
	v_bitop3_b32 v0, v11, 7, v3 bitop3:0x48
	v_lshl_add_u64 v[70:71], s[6:7], 0, v[4:5]
	v_mov_b32_e32 v4, 0
	v_add_u32_e32 v87, 0x10000, v79
	v_add_u32_e32 v88, 0x18000, v79
	v_lshlrev_b32_e32 v91, 4, v1
	v_add_u32_e32 v93, 0x10000, v80
	v_or_b32_e32 v94, 0x18000, v81
	v_add_u32_e32 v95, 0x12000, v79
	v_add_u32_e32 v96, 0x1a000, v79
	v_add_u32_e32 v97, 0x14000, v79
	v_add_u32_e32 v98, 0x16000, v79
	v_lshlrev_b32_e32 v0, 4, v0
	v_mov_b32_e32 v1, v2
	s_mov_b32 s1, 0
	v_mov_b32_e32 v5, v4
	v_mov_b64_e32 v[6:7], v[4:5]
	v_mov_b64_e32 v[8:9], v[4:5]
	v_mov_b64_e32 v[10:11], v[4:5]
	v_mov_b64_e32 v[12:13], v[4:5]
	v_mov_b64_e32 v[14:15], v[4:5]
	v_mov_b64_e32 v[16:17], v[4:5]
	v_mov_b64_e32 v[18:19], v[4:5]
	v_mov_b64_e32 v[20:21], v[4:5]
	v_mov_b64_e32 v[22:23], v[4:5]
	v_mov_b64_e32 v[24:25], v[4:5]
	v_mov_b64_e32 v[26:27], v[4:5]
	v_mov_b64_e32 v[28:29], v[4:5]
	v_mov_b64_e32 v[30:31], v[4:5]
	v_mov_b64_e32 v[32:33], v[4:5]
	v_mov_b64_e32 v[34:35], v[4:5]
	v_mov_b64_e32 v[36:37], v[4:5]
	v_mov_b64_e32 v[38:39], v[4:5]
	v_mov_b64_e32 v[40:41], v[4:5]
	v_mov_b64_e32 v[42:43], v[4:5]
	v_mov_b64_e32 v[44:45], v[4:5]
	v_mov_b64_e32 v[46:47], v[4:5]
	v_mov_b64_e32 v[48:49], v[4:5]
	v_mov_b64_e32 v[50:51], v[4:5]
	v_mov_b64_e32 v[52:53], v[4:5]
	v_mov_b64_e32 v[54:55], v[4:5]
	v_mov_b64_e32 v[56:57], v[4:5]
	v_mov_b64_e32 v[58:59], v[4:5]
	v_mov_b64_e32 v[60:61], v[4:5]
	v_mov_b64_e32 v[62:63], v[4:5]
	v_mov_b64_e32 v[64:65], v[4:5]
	v_mov_b64_e32 v[66:67], v[4:5]
	s_waitcnt vmcnt(0) lgkmcnt(0)
	s_barrier
	s_branch .LBB0_1248

; DI int tid_opaque() { int t = threadIdx.x; asm volatile("" : "+v"(t)); return t; }
; #define WAIT_V8(n) asm volatile("s_waitcnt vmcnt(" #n ")" ::: "memory")
; #define BAR8 __builtin_amdgcn_s_barrier()
;   constexpr int HT = 128 * 64;
;   bf16_t* shm = (bf16_t*)smem;
;   const int t = tid_opaque();
;     ...
;   if (wr == 1) BAR8;
;   WAIT_V8(4); BAR8;
;   STAGE8(SB8(1, 0), Bt, K, bcol, 1); STAGE8(SA8(1, 0), A, lda, brow, 1); STAGE8(SB8(1, 1), Bt, K, bcol + 128, 1);
.LBB0_1258:
	s_or_b64 exec, exec, s[8:9]
	v_add_u32_e32 v0, v150, v0
	v_and_b32_e32 v0, 0xfffffc00, v0
	v_sub_u32_e32 v0, v150, v0
	v_lshrrev_b32_e32 v6, 4, v0
	v_add_u32_e32 v1, v3, v1
	v_bitop3_b32 v7, v6, v0, 32 bitop3:0x6c
	v_ashrrev_i32_e32 v0, 31, v0
	v_ashrrev_i32_e32 v1, 6, v1
	v_lshrrev_b32_e32 v0, 26, v0
	v_lshlrev_b32_e32 v6, 3, v1
	v_add_u32_e32 v0, v7, v0
	v_and_b32_e32 v6, -16, v6
	v_ashrrev_i32_e32 v0, 6, v0
	s_and_b32 s1, s12, 63
	s_and_b32 s8, s20, 0xffffff00
	v_add_u32_e32 v6, v0, v6
	v_mul_i32_i24_e32 v0, 64, v0
	s_lshl_b32 s12, s1, 19
	s_ashr_i32 s9, s8, 31
	s_ashr_i32 s1, s0, 31
	v_lshlrev_b32_e32 v1, 5, v1
	v_sub_u32_e32 v0, v7, v0
	v_mov_b32_e32 v13, 1
	s_lshl_b64 s[14:15], s[8:9], 11
	s_lshl_b64 s[8:9], s[0:1], 11
	v_and_b32_e32 v1, 32, v1
	v_ashrrev_i16_sdwa v0, v13, sext(v0) dst_sel:DWORD dst_unused:UNUSED_PAD src0_sel:DWORD src1_sel:BYTE_0
	s_add_u32 s8, s4, s8
	v_add_u32_sdwa v0, v1, sext(v0) dst_sel:DWORD dst_unused:UNUSED_PAD src0_sel:DWORD src1_sel:WORD_0
	v_ashrrev_i32_e32 v7, 31, v6
	v_readlane_b32 s40, v254, 35
	s_addc_u32 s9, s5, s9
	v_lshlrev_b64 v[132:133], 11, v[6:7]
	v_ashrrev_i32_e32 v1, 31, v0
	v_readlane_b32 s41, v254, 36
	v_lshl_add_u64 v[6:7], s[8:9], 0, v[132:133]
	v_lshlrev_b64 v[8:9], 1, v[0:1]
	v_add_u32_e32 v164, 0x18000, v150
	s_mov_b32 s13, s40
	v_lshl_add_u64 v[6:7], v[6:7], 0, v[8:9]
	s_mov_b64 s[40:41], 0x80
	v_readfirstlane_b32 s1, v164
	v_lshl_add_u64 v[6:7], v[6:7], 0, s[40:41]
	s_mov_b32 m0, s1
	s_waitcnt vmcnt(4)
	s_barrier
; #define WAIT_V8(n) asm volatile("s_waitcnt vmcnt(" #n ")" ::: "memory")
; #define BAR8 __builtin_amdgcn_s_barrier()
;     ...
;   f32x4 acc[2][2][4][2];
;   {
;     float zinit = 0.f;
;     asm volatile("" : "+v"(zinit));
; #pragma unroll
;     for (int a = 0; a < 2; ++a)
; #pragma unroll
;       for (int b = 0; b < 2; ++b)
; #pragma unroll
;         for (int m = 0; m < 4; ++m)
; #pragma unroll
;           for (int n = 0; n < 2; ++n)
; #pragma unroll
;             for (int j = 0; j < 4; ++j) acc[a][b][m][n][j] = zinit;
;   }
;   bf16x8 At[4][2], B0[2][2], B1[2][2];
;   const int nt = K / 64;
;   if (!pre) {
;     STAGE8(SB8(0, 0), Bt, K, bcol, 0); STAGE8(SA8(0, 0), A, lda, brow, 0);
;     STAGE8(SB8(0, 1), Bt, K, bcol + 128, 0); STAGE8(SA8(0, 1), A, lda, brow + 128, 0);
;   }
;   if (wr == 1) BAR8;
;   WAIT_V8(4); BAR8;
;   STAGE8(SB8(1, 0), Bt, K, bcol, 1); STAGE8(SA8(1, 0), A, lda, brow, 1); STAGE8(SB8(1, 1), Bt, K, bcol + 128, 1);
;   WAIT_V8(6); BAR8;
	global_load_lds_dwordx4 v[6:7], off
	v_ashrrev_i32_e32 v6, 31, v152
	v_lshrrev_b32_e32 v6, 22, v6
	v_add_u32_e32 v6, v152, v6
	v_ashrrev_i32_e32 v7, 10, v6
	v_mul_i32_i24_e32 v6, 0x400, v7
	v_sub_u32_e32 v6, v152, v6
	v_lshrrev_b32_e32 v10, 4, v6
	v_bitop3_b32 v10, v10, v6, 32 bitop3:0x6c
	v_ashrrev_i32_e32 v11, 31, v10
	v_lshrrev_b32_e32 v11, 26, v11
	v_add_u32_e32 v11, v10, v11
	v_lshlrev_b32_e32 v6, 3, v7
	v_ashrrev_i32_e32 v12, 6, v11
	v_and_b32_e32 v11, 0xc0, v11
	v_and_b32_e32 v6, -16, v6
	v_lshlrev_b32_e32 v7, 5, v7
	v_sub_u32_e32 v10, v10, v11
	v_add_u32_e32 v6, v12, v6
	v_and_b32_e32 v7, 32, v7
	v_ashrrev_i16_sdwa v10, v13, sext(v10) dst_sel:DWORD dst_unused:UNUSED_PAD src0_sel:DWORD src1_sel:BYTE_0
	v_add_u32_sdwa v134, v7, sext(v10) dst_sel:DWORD dst_unused:UNUSED_PAD src0_sel:DWORD src1_sel:WORD_0
	v_ashrrev_i32_e32 v7, 31, v6
	v_add_u32_e32 v165, 0x1a000, v150
	v_lshlrev_b64 v[136:137], 11, v[6:7]
	v_ashrrev_i32_e32 v135, 31, v134
	v_readfirstlane_b32 s1, v165
	v_lshl_add_u64 v[6:7], s[8:9], 0, v[136:137]
	v_lshlrev_b64 v[10:11], 1, v[134:135]
	s_mov_b32 m0, s1
	s_lshl_b32 s1, s27, 11
	v_lshl_add_u64 v[6:7], v[6:7], 0, v[10:11]
	s_waitcnt lgkmcnt(0)
	s_add_u32 s8, s2, s1
	v_lshl_add_u64 v[6:7], v[6:7], 0, s[40:41]
	s_addc_u32 s9, s3, 0
	global_load_lds_dwordx4 v[6:7], off
	v_lshl_add_u64 v[6:7], s[8:9], 0, v[132:133]
	v_add_u32_e32 v166, 0x8000, v150
	v_lshl_add_u64 v[6:7], v[6:7], 0, v[8:9]
	v_readfirstlane_b32 s1, v166
	s_or_b32 s36, s0, 0x80
	v_lshl_add_u64 v[6:7], v[6:7], 0, s[40:41]
	s_mov_b32 m0, s1
	s_ashr_i32 s37, s36, 31
	global_load_lds_dwordx4 v[6:7], off
	v_lshl_add_u64 v[6:7], s[8:9], 0, v[136:137]
	v_add_u32_e32 v167, 0xa000, v150
	s_lshl_b64 s[36:37], s[36:37], 11
	v_lshl_add_u64 v[6:7], v[6:7], 0, v[10:11]
	v_readfirstlane_b32 s1, v167
	s_add_u32 s36, s4, s36
	v_lshl_add_u64 v[6:7], v[6:7], 0, s[40:41]
	s_mov_b32 m0, s1
	s_addc_u32 s37, s5, s37
	global_load_lds_dwordx4 v[6:7], off
	v_lshl_add_u64 v[6:7], s[36:37], 0, v[132:133]
	v_add_u32_e32 v168, 0x1c000, v150
	v_lshl_add_u64 v[6:7], v[6:7], 0, v[8:9]
	v_readfirstlane_b32 s1, v168
	v_lshl_add_u64 v[6:7], v[6:7], 0, s[40:41]
	s_mov_b32 m0, s1
	v_add_u32_e32 v170, 0x1e000, v150
	global_load_lds_dwordx4 v[6:7], off
	v_lshl_add_u64 v[6:7], s[36:37], 0, v[136:137]
	v_lshl_add_u64 v[6:7], v[6:7], 0, v[10:11]
	v_readfirstlane_b32 s1, v170
	v_lshl_add_u64 v[6:7], v[6:7], 0, s[40:41]
	s_mov_b32 m0, s1
	v_and_b32_e32 v147, 15, v3
	global_load_lds_dwordx4 v[6:7], off
	v_bfe_u32 v148, v3, 4, 2
	v_lshlrev_b32_e32 v6, 4, v148
	v_lshlrev_b32_e32 v7, 6, v147
	v_lshlrev_b32_e32 v14, 2, v3
	v_or_b32_e32 v13, v6, v7
	v_and_b32_e32 v14, 32, v14
	s_mov_b32 s1, 0x10000
	v_bitop3_b32 v16, v13, s1, v14 bitop3:0xde
	s_mov_b32 s1, 0x14000
	v_bitop3_b32 v15, v6, v14, v7 bitop3:0x36
	v_bitop3_b32 v17, v13, s1, v14 bitop3:0xde
	s_mov_b32 s1, 0x18000
	v_lshlrev_b32_e32 v7, 6, v3
	v_bitop3_b32 v18, v13, s1, v14 bitop3:0xde
	s_mov_b32 s1, 0x1c000
	v_and_b32_e32 v7, 0x3c0, v7
	v_bitop3_b32 v13, v13, s1, v14 bitop3:0xde
	v_bitop3_b32 v14, v7, v14, v6 bitop3:0x36
	v_lshl_add_u64 v[6:7], s[12:13], 0, v[132:133]
	v_lshl_add_u64 v[6:7], v[6:7], 0, v[8:9]
	v_lshl_add_u64 v[138:139], s[2:3], 0, v[6:7]
	v_lshl_add_u64 v[6:7], s[12:13], 0, v[136:137]
	v_lshl_add_u64 v[6:7], v[6:7], 0, v[10:11]
	v_lshl_add_u64 v[140:141], s[2:3], 0, v[6:7]
	v_lshl_add_u64 v[6:7], s[14:15], 0, v[132:133]
	v_lshl_add_u64 v[6:7], v[6:7], 0, v[8:9]
	v_bfe_u32 v146, v3, 6, 2
	s_waitcnt vmcnt(6)
	v_lshlrev_b32_e32 v149, 6, v5
	v_lshlrev_b32_e32 v5, 13, v5
	v_lshl_add_u64 v[142:143], s[6:7], 0, v[6:7]
	v_lshl_add_u64 v[6:7], s[14:15], 0, v[136:137]
	v_readlane_b32 s42, v254, 37
	v_readlane_b32 s43, v254, 38
	v_lshlrev_b32_e32 v12, 12, v146
	v_or_b32_e32 v19, 0x800, v5
	v_or_b32_e32 v20, 0x1000, v5
	v_or_b32_e32 v21, 0x1800, v5
	v_lshl_add_u64 v[6:7], v[6:7], 0, v[10:11]
	v_lshl_add_u64 v[144:145], s[6:7], 0, v[6:7]
	s_mov_b32 s1, -2
	s_mov_b64 s[12:13], 0
	v_add_u32_e32 v171, v16, v12
	v_add_u32_e32 v161, v15, v5
	v_add_u32_e32 v160, v14, v19
	v_add_u32_e32 v159, v14, v20
	v_add_u32_e32 v158, v14, v21
	v_add_u32_e32 v169, v17, v12
	v_add_u32_e32 v163, v18, v12
	v_add_u32_e32 v162, v13, v12
	v_mov_b32_e32 v5, v4
	v_mov_b64_e32 v[6:7], v[4:5]
	v_mov_b64_e32 v[8:9], v[4:5]
	v_mov_b64_e32 v[10:11], v[4:5]
	v_mov_b64_e32 v[12:13], v[4:5]
	v_mov_b64_e32 v[14:15], v[4:5]
	v_mov_b64_e32 v[16:17], v[4:5]
	v_mov_b64_e32 v[18:19], v[4:5]
	v_mov_b64_e32 v[20:21], v[4:5]
	v_mov_b64_e32 v[22:23], v[4:5]
	v_mov_b64_e32 v[24:25], v[4:5]
	v_mov_b64_e32 v[26:27], v[4:5]
	v_mov_b64_e32 v[28:29], v[4:5]
	v_mov_b64_e32 v[30:31], v[4:5]
	v_mov_b64_e32 v[32:33], v[4:5]
	v_mov_b64_e32 v[34:35], v[4:5]
	v_mov_b64_e32 v[36:37], v[4:5]
	v_mov_b64_e32 v[38:39], v[4:5]
	v_mov_b64_e32 v[40:41], v[4:5]
	v_mov_b64_e32 v[42:43], v[4:5]
	v_mov_b64_e32 v[44:45], v[4:5]
	v_mov_b64_e32 v[46:47], v[4:5]
	v_mov_b64_e32 v[48:49], v[4:5]
	v_mov_b64_e32 v[50:51], v[4:5]
	v_mov_b64_e32 v[52:53], v[4:5]
	v_mov_b64_e32 v[54:55], v[4:5]
	v_mov_b64_e32 v[56:57], v[4:5]
	v_mov_b64_e32 v[58:59], v[4:5]
	v_mov_b64_e32 v[60:61], v[4:5]
	v_mov_b64_e32 v[62:63], v[4:5]
	v_mov_b64_e32 v[64:65], v[4:5]
	v_mov_b64_e32 v[66:67], v[4:5]
	v_mov_b64_e32 v[68:69], v[4:5]
	v_mov_b64_e32 v[70:71], v[4:5]
	v_mov_b64_e32 v[72:73], v[4:5]
	v_mov_b64_e32 v[74:75], v[4:5]
	v_mov_b64_e32 v[76:77], v[4:5]
	v_mov_b64_e32 v[78:79], v[4:5]
	v_mov_b64_e32 v[80:81], v[4:5]
	v_mov_b64_e32 v[82:83], v[4:5]
	v_mov_b64_e32 v[84:85], v[4:5]
	v_mov_b64_e32 v[86:87], v[4:5]
	v_mov_b64_e32 v[88:89], v[4:5]
	v_mov_b64_e32 v[90:91], v[4:5]
	v_mov_b64_e32 v[92:93], v[4:5]
	v_mov_b64_e32 v[94:95], v[4:5]
	v_mov_b64_e32 v[96:97], v[4:5]
	v_mov_b64_e32 v[98:99], v[4:5]
	v_mov_b64_e32 v[100:101], v[4:5]
	v_mov_b64_e32 v[102:103], v[4:5]
	v_mov_b64_e32 v[104:105], v[4:5]
	v_mov_b64_e32 v[106:107], v[4:5]
	v_mov_b64_e32 v[108:109], v[4:5]
	v_mov_b64_e32 v[110:111], v[4:5]
	v_mov_b64_e32 v[112:113], v[4:5]
	v_mov_b64_e32 v[114:115], v[4:5]
	v_mov_b64_e32 v[116:117], v[4:5]
	v_mov_b64_e32 v[118:119], v[4:5]
	v_mov_b64_e32 v[120:121], v[4:5]
	v_mov_b64_e32 v[122:123], v[4:5]
	v_mov_b64_e32 v[124:125], v[4:5]
	v_mov_b64_e32 v[126:127], v[4:5]
	v_mov_b64_e32 v[128:129], v[4:5]
	v_mov_b64_e32 v[130:131], v[4:5]
	s_mov_b64 s[36:37], 0xcaa0100
	s_mov_b64 s[40:41], 0xcae0100
	s_mov_b64 s[42:43], 0xcaa0180
	s_mov_b64 s[44:45], 0xcae0180
	s_barrier

; #define WAIT_V8(n) asm volatile("s_waitcnt vmcnt(" #n ")" ::: "memory")
; #define BAR8 __builtin_amdgcn_s_barrier()
;     ...
;   f32x4 acc[2][2][4][2];
;   {
;     float zinit = 0.f;
;     asm volatile("" : "+v"(zinit));
; #pragma unroll
;     for (int a = 0; a < 2; ++a)
; #pragma unroll
;       for (int b = 0; b < 2; ++b)
; #pragma unroll
;         for (int m = 0; m < 4; ++m)
; #pragma unroll
;           for (int n = 0; n < 2; ++n)
; #pragma unroll
;             for (int j = 0; j < 4; ++j) acc[a][b][m][n][j] = zinit;
;   }
;   bf16x8 At[4][2], B0[2][2], B1[2][2];
;   const int nt = K / 64;
;   if (!pre) {
;     STAGE8(SB8(0, 0), Bt, K, bcol, 0); STAGE8(SA8(0, 0), A, lda, brow, 0);
;     STAGE8(SB8(0, 1), Bt, K, bcol + 128, 0); STAGE8(SA8(0, 1), A, lda, brow + 128, 0);
;   }
;   if (wr == 1) BAR8;
;   WAIT_V8(4); BAR8;
;   STAGE8(SB8(1, 0), Bt, K, bcol, 1); STAGE8(SA8(1, 0), A, lda, brow, 1); STAGE8(SB8(1, 1), Bt, K, bcol + 128, 1);
;   WAIT_V8(6); BAR8;
.LBB0_1324:
	s_or_b64 exec, exec, s[12:13]
	v_add_u32_e32 v164, 0x18000, v150
	s_mov_b64 s[36:37], 0x80
	v_readfirstlane_b32 s12, v164
	v_add_u32_e32 v165, 0x1a000, v150
	v_lshl_add_u64 v[10:11], v[10:11], 0, s[36:37]
	s_mov_b32 m0, s12
	v_readfirstlane_b32 s12, v165
	v_add_u32_e32 v166, 0x8000, v150
	s_waitcnt vmcnt(4)
	s_barrier
	global_load_lds_dwordx4 v[10:11], off
	v_lshl_add_u64 v[10:11], v[12:13], 0, s[36:37]
	s_mov_b32 m0, s12
	v_readfirstlane_b32 s12, v166
	v_add_u32_e32 v167, 0xa000, v150
	global_load_lds_dwordx4 v[10:11], off
	v_lshl_add_u64 v[10:11], v[14:15], 0, s[36:37]
	s_mov_b32 m0, s12
	v_readfirstlane_b32 s12, v167
	v_add_u32_e32 v168, 0x1c000, v150
	global_load_lds_dwordx4 v[10:11], off
	v_lshl_add_u64 v[10:11], v[16:17], 0, s[36:37]
	s_mov_b32 m0, s12
	v_readfirstlane_b32 s12, v168
	v_add_u32_e32 v170, 0x1e000, v150
	global_load_lds_dwordx4 v[10:11], off
	v_lshl_add_u64 v[10:11], v[18:19], 0, s[36:37]
	s_mov_b32 m0, s12
	v_readfirstlane_b32 s12, v170
	global_load_lds_dwordx4 v[10:11], off
	v_lshl_add_u64 v[10:11], v[20:21], 0, s[36:37]
	s_mov_b32 m0, s12
	v_and_b32_e32 v147, 15, v3
	global_load_lds_dwordx4 v[10:11], off
	v_bfe_u32 v148, v3, 4, 2
	v_lshlrev_b32_e32 v10, 4, v148
	v_lshlrev_b32_e32 v11, 6, v147
	v_lshlrev_b32_e32 v13, 2, v3
	v_or_b32_e32 v12, v10, v11
	v_and_b32_e32 v13, 32, v13
	s_mov_b32 s12, 0x10000
	v_bitop3_b32 v18, v12, s12, v13 bitop3:0xde
	s_mov_b32 s12, 0x14000
	v_bitop3_b32 v17, v10, v13, v11 bitop3:0x36
	v_bitop3_b32 v19, v12, s12, v13 bitop3:0xde
	s_mov_b32 s12, 0x18000
	v_lshlrev_b32_e32 v11, 6, v3
	v_bitop3_b32 v20, v12, s12, v13 bitop3:0xde
	s_mov_b32 s12, 0x1c000
	v_and_b32_e32 v11, 0x3c0, v11
	s_movk_i32 s31, 0x1600
	s_and_b32 s29, s21, 0xffffff00
	v_bitop3_b32 v21, v12, s12, v13 bitop3:0xde
	v_bitop3_b32 v24, v11, v13, v10 bitop3:0x36
	v_mad_i64_i32 v[10:11], s[12:13], v5, s31, 0
	v_mov_b32_e32 v5, 0x1600
	v_mad_i64_i32 v[12:13], s[12:13], s29, v5, v[10:11]
	v_lshl_add_u64 v[12:13], v[12:13], 0, v[6:7]
	v_lshl_add_u64 v[138:139], s[4:5], 0, v[12:13]
	v_mad_i64_i32 v[12:13], s[12:13], v22, s31, 0
	v_mad_i64_i32 v[14:15], s[12:13], s29, v5, v[12:13]
	s_bfe_u32 s29, s20, 0x60008
	v_mov_b32_e32 v5, 0x160000
	v_mad_u64_u32 v[10:11], s[12:13], s29, v5, v[10:11]
	v_lshl_add_u64 v[6:7], v[10:11], 0, v[6:7]
	v_bfe_u32 v146, v3, 6, 2
	s_waitcnt vmcnt(6)
	v_lshlrev_b32_e32 v149, 6, v23
	v_lshlrev_b32_e32 v23, 13, v23
	v_lshl_add_u64 v[142:143], s[2:3], 0, v[6:7]
	v_mad_u64_u32 v[6:7], s[12:13], s29, v5, v[12:13]
	v_lshlrev_b32_e32 v16, 12, v146
	v_or_b32_e32 v25, 0x800, v23
	v_or_b32_e32 v26, 0x1000, v23
	v_or_b32_e32 v27, 0x1800, v23
	v_lshl_add_u64 v[14:15], v[14:15], 0, v[8:9]
	v_lshl_add_u64 v[6:7], v[6:7], 0, v[8:9]
	s_ashr_i32 s9, s8, 31
	v_lshl_add_u64 v[140:141], s[4:5], 0, v[14:15]
	v_lshl_add_u64 v[144:145], s[2:3], 0, v[6:7]
	s_mov_b32 s29, -2
	s_mov_b64 s[12:13], 0
	v_add_u32_e32 v171, v18, v16
	v_add_u32_e32 v156, v17, v23
	v_add_u32_e32 v155, v24, v25
	v_add_u32_e32 v154, v24, v26
	v_add_u32_e32 v153, v24, v27
	v_add_u32_e32 v169, v19, v16
	v_add_u32_e32 v159, v20, v16
	v_add_u32_e32 v158, v21, v16
	v_mov_b32_e32 v5, v4
	v_mov_b64_e32 v[6:7], v[4:5]
	v_mov_b64_e32 v[8:9], v[4:5]
	v_mov_b64_e32 v[10:11], v[4:5]
	v_mov_b64_e32 v[12:13], v[4:5]
	v_mov_b64_e32 v[14:15], v[4:5]
	v_mov_b64_e32 v[16:17], v[4:5]
	v_mov_b64_e32 v[18:19], v[4:5]
	v_mov_b64_e32 v[20:21], v[4:5]
	v_mov_b64_e32 v[22:23], v[4:5]
	v_mov_b64_e32 v[24:25], v[4:5]
	v_mov_b64_e32 v[26:27], v[4:5]
	v_mov_b64_e32 v[28:29], v[4:5]
	v_mov_b64_e32 v[30:31], v[4:5]
	v_mov_b64_e32 v[32:33], v[4:5]
	v_mov_b64_e32 v[34:35], v[4:5]
	v_mov_b64_e32 v[36:37], v[4:5]
	v_mov_b64_e32 v[38:39], v[4:5]
	v_mov_b64_e32 v[40:41], v[4:5]
	v_mov_b64_e32 v[42:43], v[4:5]
	v_mov_b64_e32 v[44:45], v[4:5]
	v_mov_b64_e32 v[46:47], v[4:5]
	v_mov_b64_e32 v[48:49], v[4:5]
	v_mov_b64_e32 v[50:51], v[4:5]
	v_mov_b64_e32 v[52:53], v[4:5]
	v_mov_b64_e32 v[54:55], v[4:5]
	v_mov_b64_e32 v[56:57], v[4:5]
	v_mov_b64_e32 v[58:59], v[4:5]
	v_mov_b64_e32 v[60:61], v[4:5]
	v_mov_b64_e32 v[62:63], v[4:5]
	v_mov_b64_e32 v[64:65], v[4:5]
	v_mov_b64_e32 v[66:67], v[4:5]
	v_mov_b64_e32 v[68:69], v[4:5]
	v_mov_b64_e32 v[70:71], v[4:5]
	v_mov_b64_e32 v[72:73], v[4:5]
	v_mov_b64_e32 v[74:75], v[4:5]
	v_mov_b64_e32 v[76:77], v[4:5]
	v_mov_b64_e32 v[78:79], v[4:5]
	v_mov_b64_e32 v[80:81], v[4:5]
	v_mov_b64_e32 v[82:83], v[4:5]
	v_mov_b64_e32 v[84:85], v[4:5]
	v_mov_b64_e32 v[86:87], v[4:5]
	v_mov_b64_e32 v[88:89], v[4:5]
	v_mov_b64_e32 v[90:91], v[4:5]
	v_mov_b64_e32 v[92:93], v[4:5]
	v_mov_b64_e32 v[94:95], v[4:5]
	v_mov_b64_e32 v[96:97], v[4:5]
	v_mov_b64_e32 v[98:99], v[4:5]
	v_mov_b64_e32 v[100:101], v[4:5]
	v_mov_b64_e32 v[102:103], v[4:5]
	v_mov_b64_e32 v[104:105], v[4:5]
	v_mov_b64_e32 v[106:107], v[4:5]
	v_mov_b64_e32 v[108:109], v[4:5]
	v_mov_b64_e32 v[110:111], v[4:5]
	v_mov_b64_e32 v[112:113], v[4:5]
	v_mov_b64_e32 v[114:115], v[4:5]
	v_mov_b64_e32 v[116:117], v[4:5]
	v_mov_b64_e32 v[118:119], v[4:5]
	v_mov_b64_e32 v[120:121], v[4:5]
	v_mov_b64_e32 v[122:123], v[4:5]
	v_mov_b64_e32 v[124:125], v[4:5]
	v_mov_b64_e32 v[126:127], v[4:5]
	v_mov_b64_e32 v[128:129], v[4:5]
	v_mov_b64_e32 v[130:131], v[4:5]
	s_mov_b64 s[36:37], 0x20b0080
	s_mov_b64 s[38:39], 0xd5a0100
	s_mov_b64 s[40:41], 0x2000100
	s_mov_b64 s[42:43], 0xd650100
	s_mov_b64 s[44:45], 0x20b0100
	s_mov_b64 s[46:47], 0xd5a0180
	s_mov_b64 s[48:49], 0x2000180
	s_mov_b64 s[50:51], 0xd650180
	s_barrier
